# plus: K-loop LDS-DMA issue reordered (m0 write, address add, load) so the s_nop after each m0 write is gone
# speedup vs baseline: 1.0002x; 1.0002x over previous
; #define PG8_STAGE(bufoff, gbase, voff) do { _Pragma("unroll") for (int _i = 0; _i < 2; ++_i) \
;         __builtin_amdgcn_global_load_lds((const unsigned*)((const char*)(gbase) + (voff)[_i]), (PG8_LAS unsigned*)(lds + (bufoff) + ldsw + _i * 8192), 16, 0, 0); } while (0)
; #define PG8_LDA(dst, b, h) do { _Pragma("unroll") for (int m = 0; m < 4; ++m) _Pragma("unroll") for (int k = 0; k < 2; ++k) dst[m][k] = *(const PG8_LAS bf16x8*)(lds + PG8_SA(b, h) + aoff + m * 2048 + k * 1024); } while (0)
; #define PG8_LDB(dst, b, h) do { _Pragma("unroll") for (int n = 0; n < 2; ++n) _Pragma("unroll") for (int k = 0; k < 2; ++k) dst[n][k] = *(const PG8_LAS bf16x8*)(lds + PG8_SB(b, h) + boff + n * 2048 + k * 1024); } while (0)
; #define PG8_MMA(ai, bj, At, Bt) do { __builtin_amdgcn_s_setprio(1); _Pragma("unroll") for (int m = 0; m < 4; ++m) _Pragma("unroll") for (int n = 0; n < 2; ++n) _Pragma("unroll") for (int k = 0; k < 2; ++k) \
;         acc[ai][bj][m][n] = __builtin_amdgcn_mfma_f32_16x16x32_bf16(Bt[n][k], At[m][k], acc[ai][bj][m][n], 0, 0, 0); __builtin_amdgcn_s_setprio(0); } while (0)
; #define PG8_WAIT_V(n) asm volatile("s_waitcnt vmcnt(" #n ")" ::: "memory")
; #define PG8_WAIT_L(n) asm volatile("s_waitcnt lgkmcnt(" #n ")" ::: "memory")
; template <class Epi, class Sched, bool ALIGN_EPI = false, bool SP2 = false>
; __device__ __forceinline__ void gemm_phase(PG8_LAS unsigned char* lds, const Gemm g, const Sched& S, const Epi& E) {
;     ...
;             const bool last = (t == nt - 2);
;             const char* a1 = cA + (size_t)(t + 1) * kstep;
;             const char* a2 = last ? nA : cA + (size_t)(t + 2) * kstep; const char* b2 = last ? nB : cB + (size_t)(t + 2) * kstep;
;             const char* a3 = a2 + kstep; const char* b3 = b2 + kstep;
;             if (last && has_next) S.a_ready(nxt);
;             if constexpr (SP2) {
;             PG8_LDB(B0, 0, 0); PG8_LDB(B1, 0, 1); PG8_SCHED; PG8_LDA(At, 0, 0); PG8_STAGE(PG8_SA(1, 1), a1 + hstep, voffA);
;             PG8_WAIT_V(8); PG8_WAIT_L(0); PG8_BAR; PG8_MMA(0, 0, At, B0); PG8_MMA(0, 1, At, B1); PG8_BAR; PG8_SCHED;
;             PG8_LDA(At, 0, 1); PG8_STAGE(PG8_SB(0, 0), b2, voffB); PG8_STAGE(PG8_SB(0, 1), b2 + hstep, voffB); PG8_STAGE(PG8_SA(0, 0), a2, voffA);
;             PG8_WAIT_V(8); PG8_WAIT_L(0); PG8_BAR; PG8_MMA(1, 0, At, B0); PG8_MMA(1, 1, At, B1); PG8_BAR; PG8_SCHED;
.LBB0_63:
	s_add_i32 s66, s46, 2
	s_add_u32 s10, s44, 0x80
	s_addc_u32 s11, s45, 0
	s_add_i32 s67, 0, 0x10000
	s_cmp_eq_u32 s74, s46
	s_cselect_b32 s47, s63, s11
	s_cselect_b32 s46, s62, s10
	s_cselect_b32 s79, s65, s20
	s_cselect_b32 s78, s64, s19
	s_add_i32 s10, 0, 0x14000
	v_add_u32_e32 v140, s67, v183
	v_add_u32_e32 v166, s10, v183
	ds_read_b128 v[128:131], v140
	ds_read_b128 v[132:135], v140 offset:1024
	ds_read_b128 v[136:139], v140 offset:2048
	ds_read_b128 v[140:143], v140 offset:3072
	ds_read_b128 v[144:147], v166
	ds_read_b128 v[148:151], v166 offset:1024
	ds_read_b128 v[152:155], v166 offset:2048
	ds_read_b128 v[166:169], v166 offset:3072
	v_lshl_add_u64 v[190:191], s[44:45], 0, v[162:163]
	s_add_i32 m0, s23, 0xc000
	ds_read_b128 v[170:173], v185
	ds_read_b128 v[174:177], v185 offset:1024
	ds_read_b128 v[178:181], v185 offset:2048
	ds_read_b128 v[186:189], v185 offset:3072
	ds_read_b128 v[194:197], v185 offset:4096
	ds_read_b128 v[198:201], v185 offset:5120
	ds_read_b128 v[202:205], v185 offset:6144
	ds_read_b128 v[206:209], v185 offset:7168
	global_load_lds_dwordx4 v[190:191], off
	s_add_i32 m0, s23, 0xe000
	v_lshl_add_u64 v[190:191], s[44:45], 0, v[164:165]
	global_load_lds_dwordx4 v[190:191], off
	s_waitcnt vmcnt(8)
	s_waitcnt lgkmcnt(0)
	s_setprio 1
	s_barrier
	v_mfma_f32_16x16x32_bf16 v[124:127], v[128:131], v[170:173], v[124:127]
	v_mfma_f32_16x16x32_bf16 v[120:123], v[136:139], v[170:173], v[120:123]
	v_mfma_f32_16x16x32_bf16 v[108:111], v[128:131], v[178:181], v[108:111]
	v_mfma_f32_16x16x32_bf16 v[104:107], v[136:139], v[178:181], v[104:107]
	v_mfma_f32_16x16x32_bf16 v[92:95], v[128:131], v[194:197], v[92:95]
	v_mfma_f32_16x16x32_bf16 v[88:91], v[136:139], v[194:197], v[88:91]
	v_mfma_f32_16x16x32_bf16 v[76:79], v[128:131], v[202:205], v[76:79]
	v_mfma_f32_16x16x32_bf16 v[72:75], v[136:139], v[202:205], v[72:75]
	v_mfma_f32_16x16x32_bf16 v[124:127], v[132:135], v[174:177], v[124:127]
	v_mfma_f32_16x16x32_bf16 v[120:123], v[140:143], v[174:177], v[120:123]
	v_mfma_f32_16x16x32_bf16 v[108:111], v[132:135], v[186:189], v[108:111]
	v_mfma_f32_16x16x32_bf16 v[104:107], v[140:143], v[186:189], v[104:107]
	v_mfma_f32_16x16x32_bf16 v[92:95], v[132:135], v[198:201], v[92:95]
	v_mfma_f32_16x16x32_bf16 v[88:91], v[140:143], v[198:201], v[88:91]
	v_mfma_f32_16x16x32_bf16 v[76:79], v[132:135], v[206:209], v[76:79]
	v_mfma_f32_16x16x32_bf16 v[72:75], v[140:143], v[206:209], v[72:75]
	s_setprio 0
	s_setprio 1
	v_mfma_f32_16x16x32_bf16 v[116:119], v[144:147], v[170:173], v[116:119]
	v_mfma_f32_16x16x32_bf16 v[112:115], v[152:155], v[170:173], v[112:115]
	v_mfma_f32_16x16x32_bf16 v[100:103], v[144:147], v[178:181], v[100:103]
	v_mfma_f32_16x16x32_bf16 v[96:99], v[152:155], v[178:181], v[96:99]
	v_mfma_f32_16x16x32_bf16 v[84:87], v[144:147], v[194:197], v[84:87]
	v_mfma_f32_16x16x32_bf16 v[80:83], v[152:155], v[194:197], v[80:83]
	v_mfma_f32_16x16x32_bf16 v[68:71], v[144:147], v[202:205], v[68:71]
	v_mfma_f32_16x16x32_bf16 v[64:67], v[152:155], v[202:205], v[64:67]
	v_mfma_f32_16x16x32_bf16 v[116:119], v[148:151], v[174:177], v[116:119]
	v_mfma_f32_16x16x32_bf16 v[112:115], v[166:169], v[174:177], v[112:115]
	v_mfma_f32_16x16x32_bf16 v[100:103], v[148:151], v[186:189], v[100:103]
	v_mfma_f32_16x16x32_bf16 v[96:99], v[166:169], v[186:189], v[96:99]
	v_mfma_f32_16x16x32_bf16 v[84:87], v[148:151], v[198:201], v[84:87]
	v_mfma_f32_16x16x32_bf16 v[80:83], v[166:169], v[198:201], v[80:83]
	v_mfma_f32_16x16x32_bf16 v[68:71], v[148:151], v[206:209], v[68:71]
	v_mfma_f32_16x16x32_bf16 v[64:67], v[166:169], v[206:209], v[64:67]
	s_barrier
	s_setprio 0
	s_add_i32 s11, s67, s22
	v_lshl_add_u64 v[190:191], s[78:79], 0, v[192:193]
	s_mov_b32 m0, s11
	ds_read_b128 v[170:173], v185 offset:16384
	ds_read_b128 v[174:177], v185 offset:17408
	ds_read_b128 v[178:181], v185 offset:18432
	ds_read_b128 v[186:189], v185 offset:19456
	ds_read_b128 v[194:197], v185 offset:20480
	ds_read_b128 v[198:201], v185 offset:21504
	ds_read_b128 v[202:205], v185 offset:22528
	ds_read_b128 v[206:209], v185 offset:23552
	global_load_lds_dwordx4 v[190:191], off
	s_add_i32 m0, s11, 0x2000
	v_lshl_add_u64 v[210:211], s[78:79], 0, v[160:161]
	s_add_u32 s78, s78, s52
	s_addc_u32 s79, s79, 0
	s_add_i32 s10, s10, s22
	global_load_lds_dwordx4 v[210:211], off
	v_lshl_add_u64 v[212:213], s[78:79], 0, v[192:193]
	s_mov_b32 m0, s10
	v_lshl_add_u64 v[214:215], s[78:79], 0, v[160:161]
	global_load_lds_dwordx4 v[212:213], off
	s_add_i32 m0, s10, 0x2000
	v_lshl_add_u64 v[216:217], s[46:47], 0, v[156:157]
	global_load_lds_dwordx4 v[214:215], off
	s_mov_b32 m0, s23
	v_lshl_add_u64 v[218:219], s[46:47], 0, v[158:159]
	global_load_lds_dwordx4 v[216:217], off
	s_mov_b32 m0, s51
	s_nop 0
	global_load_lds_dwordx4 v[218:219], off
	s_waitcnt vmcnt(8)
	s_waitcnt lgkmcnt(0)
	s_setprio 1
	s_barrier
; #define PG8_STAGE(bufoff, gbase, voff) do { _Pragma("unroll") for (int _i = 0; _i < 2; ++_i) \
;         __builtin_amdgcn_global_load_lds((const unsigned*)((const char*)(gbase) + (voff)[_i]), (PG8_LAS unsigned*)(lds + (bufoff) + ldsw + _i * 8192), 16, 0, 0); } while (0)
; #define PG8_LDA(dst, b, h) do { _Pragma("unroll") for (int m = 0; m < 4; ++m) _Pragma("unroll") for (int k = 0; k < 2; ++k) dst[m][k] = *(const PG8_LAS bf16x8*)(lds + PG8_SA(b, h) + aoff + m * 2048 + k * 1024); } while (0)
; #define PG8_LDB(dst, b, h) do { _Pragma("unroll") for (int n = 0; n < 2; ++n) _Pragma("unroll") for (int k = 0; k < 2; ++k) dst[n][k] = *(const PG8_LAS bf16x8*)(lds + PG8_SB(b, h) + boff + n * 2048 + k * 1024); } while (0)
; #define PG8_MMA(ai, bj, At, Bt) do { __builtin_amdgcn_s_setprio(1); _Pragma("unroll") for (int m = 0; m < 4; ++m) _Pragma("unroll") for (int n = 0; n < 2; ++n) _Pragma("unroll") for (int k = 0; k < 2; ++k) \
;         acc[ai][bj][m][n] = __builtin_amdgcn_mfma_f32_16x16x32_bf16(Bt[n][k], At[m][k], acc[ai][bj][m][n], 0, 0, 0); __builtin_amdgcn_s_setprio(0); } while (0)
; #define PG8_WAIT_V(n) asm volatile("s_waitcnt vmcnt(" #n ")" ::: "memory")
; #define PG8_WAIT_L(n) asm volatile("s_waitcnt lgkmcnt(" #n ")" ::: "memory")
; #define PG8_BAR __builtin_amdgcn_s_barrier()
; #define PG8_SCHED __builtin_amdgcn_sched_barrier(0)
; template <class Epi, class Sched, bool ALIGN_EPI = false, bool SP2 = false>
; __device__ __forceinline__ void gemm_phase(PG8_LAS unsigned char* lds, const Gemm g, const Sched& S, const Epi& E) {
;     ...
;             PG8_WAIT_V(8); PG8_WAIT_L(0); PG8_BAR; PG8_MMA(1, 0, At, B0); PG8_MMA(1, 1, At, B1); PG8_BAR; PG8_SCHED;
;             PG8_LDB(B0, 1, 0); PG8_LDB(B1, 1, 1); PG8_SCHED; PG8_LDA(At, 1, 0); PG8_STAGE(PG8_SA(0, 1), a2 + hstep, voffA);
;             PG8_WAIT_V(8); PG8_WAIT_L(0); PG8_BAR; PG8_MMA(0, 0, At, B0); PG8_MMA(0, 1, At, B1); PG8_BAR; PG8_SCHED;
	v_mfma_f32_16x16x32_bf16 v[60:63], v[128:131], v[170:173], v[60:63]
	v_mfma_f32_16x16x32_bf16 v[56:59], v[136:139], v[170:173], v[56:59]
	v_mfma_f32_16x16x32_bf16 v[44:47], v[128:131], v[178:181], v[44:47]
	v_mfma_f32_16x16x32_bf16 v[40:43], v[136:139], v[178:181], v[40:43]
	v_mfma_f32_16x16x32_bf16 v[28:31], v[128:131], v[194:197], v[28:31]
	v_mfma_f32_16x16x32_bf16 v[24:27], v[136:139], v[194:197], v[24:27]
	v_mfma_f32_16x16x32_bf16 v[12:15], v[128:131], v[202:205], v[12:15]
	v_mfma_f32_16x16x32_bf16 v[8:11], v[136:139], v[202:205], v[8:11]
	v_mfma_f32_16x16x32_bf16 v[60:63], v[132:135], v[174:177], v[60:63]
	v_mfma_f32_16x16x32_bf16 v[56:59], v[140:143], v[174:177], v[56:59]
	v_mfma_f32_16x16x32_bf16 v[44:47], v[132:135], v[186:189], v[44:47]
	v_mfma_f32_16x16x32_bf16 v[40:43], v[140:143], v[186:189], v[40:43]
	v_mfma_f32_16x16x32_bf16 v[28:31], v[132:135], v[198:201], v[28:31]
	v_mfma_f32_16x16x32_bf16 v[24:27], v[140:143], v[198:201], v[24:27]
	v_mfma_f32_16x16x32_bf16 v[12:15], v[132:135], v[206:209], v[12:15]
	v_mfma_f32_16x16x32_bf16 v[8:11], v[140:143], v[206:209], v[8:11]
	s_setprio 0
	s_setprio 1
	v_mfma_f32_16x16x32_bf16 v[52:55], v[144:147], v[170:173], v[52:55]
	v_mfma_f32_16x16x32_bf16 v[48:51], v[152:155], v[170:173], v[48:51]
	v_mfma_f32_16x16x32_bf16 v[36:39], v[144:147], v[178:181], v[36:39]
	v_mfma_f32_16x16x32_bf16 v[32:35], v[152:155], v[178:181], v[32:35]
	v_mfma_f32_16x16x32_bf16 v[20:23], v[144:147], v[194:197], v[20:23]
	v_mfma_f32_16x16x32_bf16 v[16:19], v[152:155], v[194:197], v[16:19]
	v_mfma_f32_16x16x32_bf16 v[4:7], v[144:147], v[202:205], v[4:7]
	v_mfma_f32_16x16x32_bf16 v[0:3], v[152:155], v[202:205], v[0:3]
	v_mfma_f32_16x16x32_bf16 v[52:55], v[148:151], v[174:177], v[52:55]
	v_mfma_f32_16x16x32_bf16 v[48:51], v[166:169], v[174:177], v[48:51]
	v_mfma_f32_16x16x32_bf16 v[36:39], v[148:151], v[186:189], v[36:39]
	v_mfma_f32_16x16x32_bf16 v[32:35], v[166:169], v[186:189], v[32:35]
	v_mfma_f32_16x16x32_bf16 v[20:23], v[148:151], v[198:201], v[20:23]
	v_mfma_f32_16x16x32_bf16 v[16:19], v[166:169], v[198:201], v[16:19]
	v_mfma_f32_16x16x32_bf16 v[4:7], v[148:151], v[206:209], v[4:7]
	v_mfma_f32_16x16x32_bf16 v[0:3], v[166:169], v[206:209], v[0:3]
	s_barrier
	s_setprio 0
	s_add_i32 s10, 0, 0x18000
	s_add_i32 s11, 0, 0x1c000
	v_add_u32_e32 v140, s10, v183
	v_add_u32_e32 v166, s11, v183
	ds_read_b128 v[128:131], v140
	ds_read_b128 v[132:135], v140 offset:1024
	ds_read_b128 v[136:139], v140 offset:2048
	ds_read_b128 v[140:143], v140 offset:3072
	ds_read_b128 v[144:147], v166
	ds_read_b128 v[148:151], v166 offset:1024
	ds_read_b128 v[152:155], v166 offset:2048
	ds_read_b128 v[166:169], v166 offset:3072
	s_add_u32 s46, s46, s52
	s_addc_u32 s47, s47, 0
	s_mov_b32 m0, s68
	v_lshl_add_u64 v[220:221], s[46:47], 0, v[156:157]
	ds_read_b128 v[170:173], v185 offset:32768
	ds_read_b128 v[174:177], v185 offset:33792
	ds_read_b128 v[178:181], v185 offset:34816
	ds_read_b128 v[186:189], v185 offset:35840
	ds_read_b128 v[194:197], v185 offset:36864
	ds_read_b128 v[198:201], v185 offset:37888
	ds_read_b128 v[202:205], v185 offset:38912
	ds_read_b128 v[206:209], v185 offset:39936
	global_load_lds_dwordx4 v[220:221], off
	s_mov_b32 m0, s69
	v_lshl_add_u64 v[220:221], s[46:47], 0, v[158:159]
	global_load_lds_dwordx4 v[220:221], off
	s_waitcnt vmcnt(8)
	s_waitcnt lgkmcnt(0)
	s_setprio 1
	s_barrier
	v_mfma_f32_16x16x32_bf16 v[124:127], v[128:131], v[170:173], v[124:127]
	v_mfma_f32_16x16x32_bf16 v[120:123], v[136:139], v[170:173], v[120:123]
	v_mfma_f32_16x16x32_bf16 v[108:111], v[128:131], v[178:181], v[108:111]
	v_mfma_f32_16x16x32_bf16 v[104:107], v[136:139], v[178:181], v[104:107]
	v_mfma_f32_16x16x32_bf16 v[92:95], v[128:131], v[194:197], v[92:95]
	v_mfma_f32_16x16x32_bf16 v[88:91], v[136:139], v[194:197], v[88:91]
	v_mfma_f32_16x16x32_bf16 v[76:79], v[128:131], v[202:205], v[76:79]
	v_mfma_f32_16x16x32_bf16 v[72:75], v[136:139], v[202:205], v[72:75]
	v_mfma_f32_16x16x32_bf16 v[124:127], v[132:135], v[174:177], v[124:127]
	v_mfma_f32_16x16x32_bf16 v[120:123], v[140:143], v[174:177], v[120:123]
	v_mfma_f32_16x16x32_bf16 v[108:111], v[132:135], v[186:189], v[108:111]
	v_mfma_f32_16x16x32_bf16 v[104:107], v[140:143], v[186:189], v[104:107]
	v_mfma_f32_16x16x32_bf16 v[92:95], v[132:135], v[198:201], v[92:95]
	v_mfma_f32_16x16x32_bf16 v[88:91], v[140:143], v[198:201], v[88:91]
	v_mfma_f32_16x16x32_bf16 v[76:79], v[132:135], v[206:209], v[76:79]
	v_mfma_f32_16x16x32_bf16 v[72:75], v[140:143], v[206:209], v[72:75]
	s_setprio 0
	s_setprio 1
	v_mfma_f32_16x16x32_bf16 v[116:119], v[144:147], v[170:173], v[116:119]
	v_mfma_f32_16x16x32_bf16 v[112:115], v[152:155], v[170:173], v[112:115]
	v_mfma_f32_16x16x32_bf16 v[100:103], v[144:147], v[178:181], v[100:103]
	v_mfma_f32_16x16x32_bf16 v[96:99], v[152:155], v[178:181], v[96:99]
	v_mfma_f32_16x16x32_bf16 v[84:87], v[144:147], v[194:197], v[84:87]
	v_mfma_f32_16x16x32_bf16 v[80:83], v[152:155], v[194:197], v[80:83]
	v_mfma_f32_16x16x32_bf16 v[68:71], v[144:147], v[202:205], v[68:71]
	v_mfma_f32_16x16x32_bf16 v[64:67], v[152:155], v[202:205], v[64:67]
	v_mfma_f32_16x16x32_bf16 v[116:119], v[148:151], v[174:177], v[116:119]
	v_mfma_f32_16x16x32_bf16 v[112:115], v[166:169], v[174:177], v[112:115]
	v_mfma_f32_16x16x32_bf16 v[100:103], v[148:151], v[186:189], v[100:103]
	v_mfma_f32_16x16x32_bf16 v[96:99], v[166:169], v[186:189], v[96:99]
	v_mfma_f32_16x16x32_bf16 v[84:87], v[148:151], v[198:201], v[84:87]
	v_mfma_f32_16x16x32_bf16 v[80:83], v[166:169], v[198:201], v[80:83]
	v_mfma_f32_16x16x32_bf16 v[68:71], v[148:151], v[206:209], v[68:71]
	v_mfma_f32_16x16x32_bf16 v[64:67], v[166:169], v[206:209], v[64:67]
	s_barrier
; #define PG8_STAGE(bufoff, gbase, voff) do { _Pragma("unroll") for (int _i = 0; _i < 2; ++_i) \
;         __builtin_amdgcn_global_load_lds((const unsigned*)((const char*)(gbase) + (voff)[_i]), (PG8_LAS unsigned*)(lds + (bufoff) + ldsw + _i * 8192), 16, 0, 0); } while (0)
; #define PG8_LDA(dst, b, h) do { _Pragma("unroll") for (int m = 0; m < 4; ++m) _Pragma("unroll") for (int k = 0; k < 2; ++k) dst[m][k] = *(const PG8_LAS bf16x8*)(lds + PG8_SA(b, h) + aoff + m * 2048 + k * 1024); } while (0)
; #define PG8_MMA(ai, bj, At, Bt) do { __builtin_amdgcn_s_setprio(1); _Pragma("unroll") for (int m = 0; m < 4; ++m) _Pragma("unroll") for (int n = 0; n < 2; ++n) _Pragma("unroll") for (int k = 0; k < 2; ++k) \
;         acc[ai][bj][m][n] = __builtin_amdgcn_mfma_f32_16x16x32_bf16(Bt[n][k], At[m][k], acc[ai][bj][m][n], 0, 0, 0); __builtin_amdgcn_s_setprio(0); } while (0)
; #define PG8_WAIT_V(n) asm volatile("s_waitcnt vmcnt(" #n ")" ::: "memory")
; #define PG8_WAIT_L(n) asm volatile("s_waitcnt lgkmcnt(" #n ")" ::: "memory")
; #define PG8_BAR __builtin_amdgcn_s_barrier()
; #define PG8_SCHED __builtin_amdgcn_sched_barrier(0)
; template <class Epi, class Sched, bool ALIGN_EPI = false, bool SP2 = false>
; __device__ __forceinline__ void gemm_phase(PG8_LAS unsigned char* lds, const Gemm g, const Sched& S, const Epi& E) {
;     ...
;         for (int t = 0; t < nt; t += 2) {
;             const bool last = (t == nt - 2);
;             const char* a1 = cA + (size_t)(t + 1) * kstep;
;     ...
;             PG8_LDA(At, 1, 1); PG8_STAGE(PG8_SB(1, 0), b3, voffB); PG8_STAGE(PG8_SB(1, 1), b3 + hstep, voffB); PG8_STAGE(PG8_SA(1, 0), a3, voffA);
;             PG8_WAIT_V(8); PG8_WAIT_L(0); PG8_BAR; PG8_MMA(1, 0, At, B0); PG8_MMA(1, 1, At, B1); PG8_BAR; PG8_SCHED;
	s_setprio 0
	s_add_i32 s10, s10, s22
	v_lshl_add_u64 v[190:191], v[190:191], 0, s[36:37]
	s_mov_b32 m0, s10
	ds_read_b128 v[170:173], v185 offset:49152
	ds_read_b128 v[174:177], v185 offset:50176
	ds_read_b128 v[178:181], v185 offset:51200
	ds_read_b128 v[186:189], v185 offset:52224
	ds_read_b128 v[194:197], v185 offset:53248
	ds_read_b128 v[198:201], v185 offset:54272
	ds_read_b128 v[202:205], v185 offset:55296
	ds_read_b128 v[206:209], v185 offset:56320
	global_load_lds_dwordx4 v[190:191], off
	v_lshl_add_u64 v[190:191], v[210:211], 0, s[36:37]
	s_add_i32 m0, s10, 0x2000
	s_add_i32 s10, s11, s22
	global_load_lds_dwordx4 v[190:191], off
	s_mov_b32 m0, s10
	v_lshl_add_u64 v[190:191], v[212:213], 0, s[36:37]
	global_load_lds_dwordx4 v[190:191], off
	s_add_i32 m0, s10, 0x2000
	v_lshl_add_u64 v[190:191], v[214:215], 0, s[36:37]
	global_load_lds_dwordx4 v[190:191], off
	s_mov_b32 m0, s70
	v_lshl_add_u64 v[190:191], v[216:217], 0, s[36:37]
	global_load_lds_dwordx4 v[190:191], off
	s_mov_b32 m0, s71
	v_lshl_add_u64 v[190:191], v[218:219], 0, s[36:37]
	global_load_lds_dwordx4 v[190:191], off
	s_waitcnt vmcnt(8)
	s_waitcnt lgkmcnt(0)
	s_setprio 1
	s_barrier
	v_mfma_f32_16x16x32_bf16 v[60:63], v[128:131], v[170:173], v[60:63]
	v_mfma_f32_16x16x32_bf16 v[56:59], v[136:139], v[170:173], v[56:59]
	v_mfma_f32_16x16x32_bf16 v[44:47], v[128:131], v[178:181], v[44:47]
	v_mfma_f32_16x16x32_bf16 v[40:43], v[136:139], v[178:181], v[40:43]
	v_mfma_f32_16x16x32_bf16 v[28:31], v[128:131], v[194:197], v[28:31]
	v_mfma_f32_16x16x32_bf16 v[24:27], v[136:139], v[194:197], v[24:27]
	v_mfma_f32_16x16x32_bf16 v[12:15], v[128:131], v[202:205], v[12:15]
	v_mfma_f32_16x16x32_bf16 v[8:11], v[136:139], v[202:205], v[8:11]
	v_mfma_f32_16x16x32_bf16 v[60:63], v[132:135], v[174:177], v[60:63]
	v_mfma_f32_16x16x32_bf16 v[56:59], v[140:143], v[174:177], v[56:59]
	v_mfma_f32_16x16x32_bf16 v[44:47], v[132:135], v[186:189], v[44:47]
	v_mfma_f32_16x16x32_bf16 v[40:43], v[140:143], v[186:189], v[40:43]
	v_mfma_f32_16x16x32_bf16 v[28:31], v[132:135], v[198:201], v[28:31]
	v_mfma_f32_16x16x32_bf16 v[24:27], v[140:143], v[198:201], v[24:27]
	v_mfma_f32_16x16x32_bf16 v[12:15], v[132:135], v[206:209], v[12:15]
	v_mfma_f32_16x16x32_bf16 v[8:11], v[140:143], v[206:209], v[8:11]
	s_setprio 0
	s_setprio 1
	v_mfma_f32_16x16x32_bf16 v[52:55], v[144:147], v[170:173], v[52:55]
	v_mfma_f32_16x16x32_bf16 v[48:51], v[152:155], v[170:173], v[48:51]
	v_mfma_f32_16x16x32_bf16 v[36:39], v[144:147], v[178:181], v[36:39]
	v_mfma_f32_16x16x32_bf16 v[32:35], v[152:155], v[178:181], v[32:35]
	v_mfma_f32_16x16x32_bf16 v[20:23], v[144:147], v[194:197], v[20:23]
	v_mfma_f32_16x16x32_bf16 v[16:19], v[152:155], v[194:197], v[16:19]
	v_mfma_f32_16x16x32_bf16 v[4:7], v[144:147], v[202:205], v[4:7]
	v_mfma_f32_16x16x32_bf16 v[0:3], v[152:155], v[202:205], v[0:3]
	v_mfma_f32_16x16x32_bf16 v[52:55], v[148:151], v[174:177], v[52:55]
	v_mfma_f32_16x16x32_bf16 v[48:51], v[166:169], v[174:177], v[48:51]
	v_mfma_f32_16x16x32_bf16 v[36:39], v[148:151], v[186:189], v[36:39]
	v_mfma_f32_16x16x32_bf16 v[32:35], v[166:169], v[186:189], v[32:35]
	v_mfma_f32_16x16x32_bf16 v[20:23], v[148:151], v[198:201], v[20:23]
	v_mfma_f32_16x16x32_bf16 v[16:19], v[166:169], v[198:201], v[16:19]
	v_mfma_f32_16x16x32_bf16 v[4:7], v[148:151], v[206:209], v[4:7]
	v_mfma_f32_16x16x32_bf16 v[0:3], v[166:169], v[206:209], v[0:3]
	s_barrier
	s_setprio 0
	s_add_u32 s44, s44, 0x100
	s_addc_u32 s45, s45, 0
	s_add_u32 s19, s19, 0x100
	s_addc_u32 s20, s20, 0
	s_cmp_ge_u32 s66, s73
	s_mov_b32 s46, s66
	s_cbranch_scc0 .LBB0_63
	s_and_b64 vcc, exec, s[56:57]
	s_cbranch_vccz .LBB0_66
	s_barrier

; #define PG8_STAGE(bufoff, gbase, voff) do { _Pragma("unroll") for (int _i = 0; _i < 2; ++_i) \
;         __builtin_amdgcn_global_load_lds((const unsigned*)((const char*)(gbase) + (voff)[_i]), (PG8_LAS unsigned*)(lds + (bufoff) + ldsw + _i * 8192), 16, 0, 0); } while (0)
; #define PG8_LDA(dst, b, h) do { _Pragma("unroll") for (int m = 0; m < 4; ++m) _Pragma("unroll") for (int k = 0; k < 2; ++k) dst[m][k] = *(const PG8_LAS bf16x8*)(lds + PG8_SA(b, h) + aoff + m * 2048 + k * 1024); } while (0)
; #define PG8_LDB(dst, b, h) do { _Pragma("unroll") for (int n = 0; n < 2; ++n) _Pragma("unroll") for (int k = 0; k < 2; ++k) dst[n][k] = *(const PG8_LAS bf16x8*)(lds + PG8_SB(b, h) + boff + n * 2048 + k * 1024); } while (0)
; #define PG8_MMA(ai, bj, At, Bt) do { __builtin_amdgcn_s_setprio(1); _Pragma("unroll") for (int m = 0; m < 4; ++m) _Pragma("unroll") for (int n = 0; n < 2; ++n) _Pragma("unroll") for (int k = 0; k < 2; ++k) \
;         acc[ai][bj][m][n] = __builtin_amdgcn_mfma_f32_16x16x32_bf16(Bt[n][k], At[m][k], acc[ai][bj][m][n], 0, 0, 0); __builtin_amdgcn_s_setprio(0); } while (0)
; #define PG8_WAIT_V(n) asm volatile("s_waitcnt vmcnt(" #n ")" ::: "memory")
; #define PG8_WAIT_L(n) asm volatile("s_waitcnt lgkmcnt(" #n ")" ::: "memory")
; template <class Epi, class Sched, bool ALIGN_EPI = false, bool SP2 = false>
; __device__ __forceinline__ void gemm_phase(PG8_LAS unsigned char* lds, const Gemm g, const Sched& S, const Epi& E) {
;     ...
;             const bool last = (t == nt - 2);
;             const char* a1 = cA + (size_t)(t + 1) * kstep;
;             const char* a2 = last ? nA : cA + (size_t)(t + 2) * kstep; const char* b2 = last ? nB : cB + (size_t)(t + 2) * kstep;
;             const char* a3 = a2 + kstep; const char* b3 = b2 + kstep;
;             if (last && has_next) S.a_ready(nxt);
;             if constexpr (SP2) {
;             PG8_LDB(B0, 0, 0); PG8_LDB(B1, 0, 1); PG8_SCHED; PG8_LDA(At, 0, 0); PG8_STAGE(PG8_SA(1, 1), a1 + hstep, voffA);
;             PG8_WAIT_V(8); PG8_WAIT_L(0); PG8_BAR; PG8_MMA(0, 0, At, B0); PG8_MMA(0, 1, At, B1); PG8_BAR; PG8_SCHED;
;             PG8_LDA(At, 0, 1); PG8_STAGE(PG8_SB(0, 0), b2, voffB); PG8_STAGE(PG8_SB(0, 1), b2 + hstep, voffB); PG8_STAGE(PG8_SA(0, 0), a2, voffA);
;             PG8_WAIT_V(8); PG8_WAIT_L(0); PG8_BAR; PG8_MMA(1, 0, At, B0); PG8_MMA(1, 1, At, B1); PG8_BAR; PG8_SCHED;
.LBB0_200:
	s_add_u32 s10, s56, 0xfffc0080
	s_addc_u32 s11, s57, -1
	s_add_i32 s77, 0, 0x10000
	s_cmp_eq_u32 s76, 12
	s_cselect_b32 s61, s18, s11
	s_cselect_b32 s60, s19, s10
	s_cselect_b32 s59, s20, s51
	s_cselect_b32 s58, s43, s49
	s_add_i32 s10, 0, 0x14000
	v_add_u32_e32 v140, s77, v163
	v_add_u32_e32 v162, s10, v163
	ds_read_b128 v[128:131], v140
	ds_read_b128 v[132:135], v140 offset:1024
	ds_read_b128 v[136:139], v140 offset:2048
	ds_read_b128 v[140:143], v140 offset:3072
	ds_read_b128 v[166:169], v162
	ds_read_b128 v[170:173], v162 offset:1024
	ds_read_b128 v[174:177], v162 offset:2048
	ds_read_b128 v[178:181], v162 offset:3072
	v_lshl_add_u64 v[190:191], s[56:57], 0, v[158:159]
	s_add_i32 m0, s64, 0xc000
	ds_read_b128 v[182:185], v165
	ds_read_b128 v[186:189], v165 offset:1024
	ds_read_b128 v[194:197], v165 offset:2048
	ds_read_b128 v[198:201], v165 offset:3072
	ds_read_b128 v[202:205], v165 offset:4096
	ds_read_b128 v[206:209], v165 offset:5120
	ds_read_b128 v[210:213], v165 offset:6144
	ds_read_b128 v[214:217], v165 offset:7168
	global_load_lds_dwordx4 v[190:191], off
	s_add_i32 m0, s64, 0xe000
	v_lshl_add_u64 v[190:191], s[56:57], 0, v[160:161]
	global_load_lds_dwordx4 v[190:191], off
	s_waitcnt vmcnt(8)
	s_waitcnt lgkmcnt(0)
	s_setprio 1
	s_barrier
	v_mfma_f32_16x16x32_bf16 v[124:127], v[128:131], v[182:185], v[124:127]
	v_mfma_f32_16x16x32_bf16 v[120:123], v[136:139], v[182:185], v[120:123]
	v_mfma_f32_16x16x32_bf16 v[112:115], v[128:131], v[194:197], v[112:115]
	v_mfma_f32_16x16x32_bf16 v[104:107], v[136:139], v[194:197], v[104:107]
	v_mfma_f32_16x16x32_bf16 v[96:99], v[128:131], v[202:205], v[96:99]
	v_mfma_f32_16x16x32_bf16 v[88:91], v[136:139], v[202:205], v[88:91]
	v_mfma_f32_16x16x32_bf16 v[80:83], v[128:131], v[210:213], v[80:83]
	v_mfma_f32_16x16x32_bf16 v[72:75], v[136:139], v[210:213], v[72:75]
	v_mfma_f32_16x16x32_bf16 v[124:127], v[132:135], v[186:189], v[124:127]
	v_mfma_f32_16x16x32_bf16 v[120:123], v[140:143], v[186:189], v[120:123]
	v_mfma_f32_16x16x32_bf16 v[112:115], v[132:135], v[198:201], v[112:115]
	v_mfma_f32_16x16x32_bf16 v[104:107], v[140:143], v[198:201], v[104:107]
	v_mfma_f32_16x16x32_bf16 v[96:99], v[132:135], v[206:209], v[96:99]
	v_mfma_f32_16x16x32_bf16 v[88:91], v[140:143], v[206:209], v[88:91]
	v_mfma_f32_16x16x32_bf16 v[80:83], v[132:135], v[214:217], v[80:83]
	v_mfma_f32_16x16x32_bf16 v[72:75], v[140:143], v[214:217], v[72:75]
	s_setprio 0
	s_setprio 1
	v_mfma_f32_16x16x32_bf16 v[116:119], v[166:169], v[182:185], v[116:119]
	v_mfma_f32_16x16x32_bf16 v[108:111], v[174:177], v[182:185], v[108:111]
	v_mfma_f32_16x16x32_bf16 v[100:103], v[166:169], v[194:197], v[100:103]
	v_mfma_f32_16x16x32_bf16 v[92:95], v[174:177], v[194:197], v[92:95]
	v_mfma_f32_16x16x32_bf16 v[84:87], v[166:169], v[202:205], v[84:87]
	v_mfma_f32_16x16x32_bf16 v[76:79], v[174:177], v[202:205], v[76:79]
	v_mfma_f32_16x16x32_bf16 v[68:71], v[166:169], v[210:213], v[68:71]
	v_mfma_f32_16x16x32_bf16 v[64:67], v[174:177], v[210:213], v[64:67]
	v_mfma_f32_16x16x32_bf16 v[116:119], v[170:173], v[186:189], v[116:119]
	v_mfma_f32_16x16x32_bf16 v[108:111], v[178:181], v[186:189], v[108:111]
	v_mfma_f32_16x16x32_bf16 v[100:103], v[170:173], v[198:201], v[100:103]
	v_mfma_f32_16x16x32_bf16 v[92:95], v[178:181], v[198:201], v[92:95]
	v_mfma_f32_16x16x32_bf16 v[84:87], v[170:173], v[206:209], v[84:87]
	v_mfma_f32_16x16x32_bf16 v[76:79], v[178:181], v[206:209], v[76:79]
	v_mfma_f32_16x16x32_bf16 v[68:71], v[170:173], v[214:217], v[68:71]
	v_mfma_f32_16x16x32_bf16 v[64:67], v[178:181], v[214:217], v[64:67]
	s_barrier
	s_setprio 0
	s_add_i32 s11, s77, s63
	v_lshl_add_u64 v[190:191], s[58:59], 0, v[146:147]
	s_mov_b32 m0, s11
	ds_read_b128 v[182:185], v165 offset:16384
	ds_read_b128 v[186:189], v165 offset:17408
	ds_read_b128 v[194:197], v165 offset:18432
	ds_read_b128 v[198:201], v165 offset:19456
	ds_read_b128 v[202:205], v165 offset:20480
	ds_read_b128 v[206:209], v165 offset:21504
	ds_read_b128 v[210:213], v165 offset:22528
	ds_read_b128 v[214:217], v165 offset:23552
	global_load_lds_dwordx4 v[190:191], off
	s_add_i32 m0, s11, 0x2000
	s_add_u32 s78, s58, 0x40000
	v_lshl_add_u64 v[218:219], s[58:59], 0, v[150:151]
	s_addc_u32 s79, s59, 0
	s_add_i32 s10, s10, s63
	global_load_lds_dwordx4 v[218:219], off
	v_lshl_add_u64 v[220:221], s[78:79], 0, v[146:147]
	s_mov_b32 m0, s10
	v_lshl_add_u64 v[222:223], s[60:61], 0, v[148:149]
	global_load_lds_dwordx4 v[220:221], off
	s_add_i32 m0, s10, 0x2000
	v_lshl_add_u64 v[220:221], s[78:79], 0, v[150:151]
	global_load_lds_dwordx4 v[220:221], off
	s_mov_b32 m0, s64
	v_lshl_add_u64 v[220:221], s[60:61], 0, v[144:145]
	global_load_lds_dwordx4 v[220:221], off
	s_mov_b32 m0, s65
	s_nop 0
	global_load_lds_dwordx4 v[222:223], off
	s_waitcnt vmcnt(8)
	s_waitcnt lgkmcnt(0)
	s_setprio 1
	s_barrier
; #define PG8_STAGE(bufoff, gbase, voff) do { _Pragma("unroll") for (int _i = 0; _i < 2; ++_i) \
;         __builtin_amdgcn_global_load_lds((const unsigned*)((const char*)(gbase) + (voff)[_i]), (PG8_LAS unsigned*)(lds + (bufoff) + ldsw + _i * 8192), 16, 0, 0); } while (0)
; #define PG8_LDA(dst, b, h) do { _Pragma("unroll") for (int m = 0; m < 4; ++m) _Pragma("unroll") for (int k = 0; k < 2; ++k) dst[m][k] = *(const PG8_LAS bf16x8*)(lds + PG8_SA(b, h) + aoff + m * 2048 + k * 1024); } while (0)
; #define PG8_LDB(dst, b, h) do { _Pragma("unroll") for (int n = 0; n < 2; ++n) _Pragma("unroll") for (int k = 0; k < 2; ++k) dst[n][k] = *(const PG8_LAS bf16x8*)(lds + PG8_SB(b, h) + boff + n * 2048 + k * 1024); } while (0)
; #define PG8_MMA(ai, bj, At, Bt) do { __builtin_amdgcn_s_setprio(1); _Pragma("unroll") for (int m = 0; m < 4; ++m) _Pragma("unroll") for (int n = 0; n < 2; ++n) _Pragma("unroll") for (int k = 0; k < 2; ++k) \
;         acc[ai][bj][m][n] = __builtin_amdgcn_mfma_f32_16x16x32_bf16(Bt[n][k], At[m][k], acc[ai][bj][m][n], 0, 0, 0); __builtin_amdgcn_s_setprio(0); } while (0)
; #define PG8_WAIT_V(n) asm volatile("s_waitcnt vmcnt(" #n ")" ::: "memory")
; #define PG8_WAIT_L(n) asm volatile("s_waitcnt lgkmcnt(" #n ")" ::: "memory")
; #define PG8_BAR __builtin_amdgcn_s_barrier()
; #define PG8_SCHED __builtin_amdgcn_sched_barrier(0)
; template <class Epi, class Sched, bool ALIGN_EPI = false, bool SP2 = false>
; __device__ __forceinline__ void gemm_phase(PG8_LAS unsigned char* lds, const Gemm g, const Sched& S, const Epi& E) {
;     ...
;             PG8_WAIT_V(8); PG8_WAIT_L(0); PG8_BAR; PG8_MMA(1, 0, At, B0); PG8_MMA(1, 1, At, B1); PG8_BAR; PG8_SCHED;
;             PG8_LDB(B0, 1, 0); PG8_LDB(B1, 1, 1); PG8_SCHED; PG8_LDA(At, 1, 0); PG8_STAGE(PG8_SA(0, 1), a2 + hstep, voffA);
;             PG8_WAIT_V(8); PG8_WAIT_L(0); PG8_BAR; PG8_MMA(0, 0, At, B0); PG8_MMA(0, 1, At, B1); PG8_BAR; PG8_SCHED;
	v_mfma_f32_16x16x32_bf16 v[60:63], v[128:131], v[182:185], v[60:63]
	v_mfma_f32_16x16x32_bf16 v[56:59], v[136:139], v[182:185], v[56:59]
	v_mfma_f32_16x16x32_bf16 v[48:51], v[128:131], v[194:197], v[48:51]
	v_mfma_f32_16x16x32_bf16 v[40:43], v[136:139], v[194:197], v[40:43]
	v_mfma_f32_16x16x32_bf16 v[32:35], v[128:131], v[202:205], v[32:35]
	v_mfma_f32_16x16x32_bf16 v[24:27], v[136:139], v[202:205], v[24:27]
	v_mfma_f32_16x16x32_bf16 v[16:19], v[128:131], v[210:213], v[16:19]
	v_mfma_f32_16x16x32_bf16 v[8:11], v[136:139], v[210:213], v[8:11]
	v_mfma_f32_16x16x32_bf16 v[60:63], v[132:135], v[186:189], v[60:63]
	v_mfma_f32_16x16x32_bf16 v[56:59], v[140:143], v[186:189], v[56:59]
	v_mfma_f32_16x16x32_bf16 v[48:51], v[132:135], v[198:201], v[48:51]
	v_mfma_f32_16x16x32_bf16 v[40:43], v[140:143], v[198:201], v[40:43]
	v_mfma_f32_16x16x32_bf16 v[32:35], v[132:135], v[206:209], v[32:35]
	v_mfma_f32_16x16x32_bf16 v[24:27], v[140:143], v[206:209], v[24:27]
	v_mfma_f32_16x16x32_bf16 v[16:19], v[132:135], v[214:217], v[16:19]
	v_mfma_f32_16x16x32_bf16 v[8:11], v[140:143], v[214:217], v[8:11]
	s_setprio 0
	s_setprio 1
	v_mfma_f32_16x16x32_bf16 v[52:55], v[166:169], v[182:185], v[52:55]
	v_mfma_f32_16x16x32_bf16 v[44:47], v[174:177], v[182:185], v[44:47]
	v_mfma_f32_16x16x32_bf16 v[36:39], v[166:169], v[194:197], v[36:39]
	v_mfma_f32_16x16x32_bf16 v[28:31], v[174:177], v[194:197], v[28:31]
	v_mfma_f32_16x16x32_bf16 v[20:23], v[166:169], v[202:205], v[20:23]
	v_mfma_f32_16x16x32_bf16 v[12:15], v[174:177], v[202:205], v[12:15]
	v_mfma_f32_16x16x32_bf16 v[4:7], v[166:169], v[210:213], v[4:7]
	v_mfma_f32_16x16x32_bf16 v[0:3], v[174:177], v[210:213], v[0:3]
	v_mfma_f32_16x16x32_bf16 v[52:55], v[170:173], v[186:189], v[52:55]
	v_mfma_f32_16x16x32_bf16 v[44:47], v[178:181], v[186:189], v[44:47]
	v_mfma_f32_16x16x32_bf16 v[36:39], v[170:173], v[198:201], v[36:39]
	v_mfma_f32_16x16x32_bf16 v[28:31], v[178:181], v[198:201], v[28:31]
	v_mfma_f32_16x16x32_bf16 v[20:23], v[170:173], v[206:209], v[20:23]
	v_mfma_f32_16x16x32_bf16 v[12:15], v[178:181], v[206:209], v[12:15]
	v_mfma_f32_16x16x32_bf16 v[4:7], v[170:173], v[214:217], v[4:7]
	v_mfma_f32_16x16x32_bf16 v[0:3], v[178:181], v[214:217], v[0:3]
	s_barrier
	s_setprio 0
	s_add_i32 s10, 0, 0x18000
	s_add_i32 s11, 0, 0x1c000
	v_add_u32_e32 v140, s10, v163
	v_add_u32_e32 v162, s11, v163
	ds_read_b128 v[128:131], v140
	ds_read_b128 v[132:135], v140 offset:1024
	ds_read_b128 v[136:139], v140 offset:2048
	ds_read_b128 v[140:143], v140 offset:3072
	ds_read_b128 v[166:169], v162
	ds_read_b128 v[170:173], v162 offset:1024
	ds_read_b128 v[174:177], v162 offset:2048
	ds_read_b128 v[178:181], v162 offset:3072
	s_add_u32 s60, s60, 0x40000
	s_addc_u32 s61, s61, 0
	s_mov_b32 m0, s66
	v_lshl_add_u64 v[224:225], s[60:61], 0, v[144:145]
	ds_read_b128 v[182:185], v165 offset:32768
	ds_read_b128 v[186:189], v165 offset:33792
	ds_read_b128 v[194:197], v165 offset:34816
	ds_read_b128 v[198:201], v165 offset:35840
	ds_read_b128 v[202:205], v165 offset:36864
	ds_read_b128 v[206:209], v165 offset:37888
	ds_read_b128 v[210:213], v165 offset:38912
	ds_read_b128 v[214:217], v165 offset:39936
	global_load_lds_dwordx4 v[224:225], off
	s_mov_b32 m0, s67
	v_lshl_add_u64 v[224:225], s[60:61], 0, v[148:149]
	global_load_lds_dwordx4 v[224:225], off
	s_waitcnt vmcnt(8)
	s_waitcnt lgkmcnt(0)
	s_setprio 1
	s_barrier
	v_mfma_f32_16x16x32_bf16 v[124:127], v[128:131], v[182:185], v[124:127]
	v_mfma_f32_16x16x32_bf16 v[120:123], v[136:139], v[182:185], v[120:123]
	v_mfma_f32_16x16x32_bf16 v[112:115], v[128:131], v[194:197], v[112:115]
	v_mfma_f32_16x16x32_bf16 v[104:107], v[136:139], v[194:197], v[104:107]
	v_mfma_f32_16x16x32_bf16 v[96:99], v[128:131], v[202:205], v[96:99]
	v_mfma_f32_16x16x32_bf16 v[88:91], v[136:139], v[202:205], v[88:91]
	v_mfma_f32_16x16x32_bf16 v[80:83], v[128:131], v[210:213], v[80:83]
	v_mfma_f32_16x16x32_bf16 v[72:75], v[136:139], v[210:213], v[72:75]
	v_mfma_f32_16x16x32_bf16 v[124:127], v[132:135], v[186:189], v[124:127]
	v_mfma_f32_16x16x32_bf16 v[120:123], v[140:143], v[186:189], v[120:123]
	v_mfma_f32_16x16x32_bf16 v[112:115], v[132:135], v[198:201], v[112:115]
	v_mfma_f32_16x16x32_bf16 v[104:107], v[140:143], v[198:201], v[104:107]
	v_mfma_f32_16x16x32_bf16 v[96:99], v[132:135], v[206:209], v[96:99]
	v_mfma_f32_16x16x32_bf16 v[88:91], v[140:143], v[206:209], v[88:91]
	v_mfma_f32_16x16x32_bf16 v[80:83], v[132:135], v[214:217], v[80:83]
	v_mfma_f32_16x16x32_bf16 v[72:75], v[140:143], v[214:217], v[72:75]
	s_setprio 0
	s_setprio 1
	v_mfma_f32_16x16x32_bf16 v[116:119], v[166:169], v[182:185], v[116:119]
	v_mfma_f32_16x16x32_bf16 v[108:111], v[174:177], v[182:185], v[108:111]
	v_mfma_f32_16x16x32_bf16 v[100:103], v[166:169], v[194:197], v[100:103]
	v_mfma_f32_16x16x32_bf16 v[92:95], v[174:177], v[194:197], v[92:95]
	v_mfma_f32_16x16x32_bf16 v[84:87], v[166:169], v[202:205], v[84:87]
	v_mfma_f32_16x16x32_bf16 v[76:79], v[174:177], v[202:205], v[76:79]
	v_mfma_f32_16x16x32_bf16 v[68:71], v[166:169], v[210:213], v[68:71]
	v_mfma_f32_16x16x32_bf16 v[64:67], v[174:177], v[210:213], v[64:67]
	v_mfma_f32_16x16x32_bf16 v[116:119], v[170:173], v[186:189], v[116:119]
	v_mfma_f32_16x16x32_bf16 v[108:111], v[178:181], v[186:189], v[108:111]
	v_mfma_f32_16x16x32_bf16 v[100:103], v[170:173], v[198:201], v[100:103]
	v_mfma_f32_16x16x32_bf16 v[92:95], v[178:181], v[198:201], v[92:95]
	v_mfma_f32_16x16x32_bf16 v[84:87], v[170:173], v[206:209], v[84:87]
	v_mfma_f32_16x16x32_bf16 v[76:79], v[178:181], v[206:209], v[76:79]
	v_mfma_f32_16x16x32_bf16 v[68:71], v[170:173], v[214:217], v[68:71]
	v_mfma_f32_16x16x32_bf16 v[64:67], v[178:181], v[214:217], v[64:67]
	s_barrier
; #define PG8_STAGE(bufoff, gbase, voff) do { _Pragma("unroll") for (int _i = 0; _i < 2; ++_i) \
;         __builtin_amdgcn_global_load_lds((const unsigned*)((const char*)(gbase) + (voff)[_i]), (PG8_LAS unsigned*)(lds + (bufoff) + ldsw + _i * 8192), 16, 0, 0); } while (0)
; #define PG8_LDA(dst, b, h) do { _Pragma("unroll") for (int m = 0; m < 4; ++m) _Pragma("unroll") for (int k = 0; k < 2; ++k) dst[m][k] = *(const PG8_LAS bf16x8*)(lds + PG8_SA(b, h) + aoff + m * 2048 + k * 1024); } while (0)
; #define PG8_MMA(ai, bj, At, Bt) do { __builtin_amdgcn_s_setprio(1); _Pragma("unroll") for (int m = 0; m < 4; ++m) _Pragma("unroll") for (int n = 0; n < 2; ++n) _Pragma("unroll") for (int k = 0; k < 2; ++k) \
;         acc[ai][bj][m][n] = __builtin_amdgcn_mfma_f32_16x16x32_bf16(Bt[n][k], At[m][k], acc[ai][bj][m][n], 0, 0, 0); __builtin_amdgcn_s_setprio(0); } while (0)
; #define PG8_WAIT_V(n) asm volatile("s_waitcnt vmcnt(" #n ")" ::: "memory")
; #define PG8_WAIT_L(n) asm volatile("s_waitcnt lgkmcnt(" #n ")" ::: "memory")
; #define PG8_BAR __builtin_amdgcn_s_barrier()
; #define PG8_SCHED __builtin_amdgcn_sched_barrier(0)
; template <class Epi, class Sched, bool ALIGN_EPI = false, bool SP2 = false>
; __device__ __forceinline__ void gemm_phase(PG8_LAS unsigned char* lds, const Gemm g, const Sched& S, const Epi& E) {
;     ...
;             PG8_LDA(At, 1, 1); PG8_STAGE(PG8_SB(1, 0), b3, voffB); PG8_STAGE(PG8_SB(1, 1), b3 + hstep, voffB); PG8_STAGE(PG8_SA(1, 0), a3, voffA);
;             PG8_WAIT_V(8); PG8_WAIT_L(0); PG8_BAR; PG8_MMA(1, 0, At, B0); PG8_MMA(1, 1, At, B1); PG8_BAR; PG8_SCHED;
;     ...
;         if constexpr (ALIGN_EPI) { if (wr == 0) PG8_BAR; }
	s_setprio 0
	s_add_i32 s10, s10, s63
	v_lshl_add_u64 v[190:191], v[190:191], 0, s[36:37]
	s_mov_b32 m0, s10
	ds_read_b128 v[182:185], v165 offset:49152
	ds_read_b128 v[186:189], v165 offset:50176
	ds_read_b128 v[194:197], v165 offset:51200
	ds_read_b128 v[198:201], v165 offset:52224
	ds_read_b128 v[202:205], v165 offset:53248
	ds_read_b128 v[206:209], v165 offset:54272
	ds_read_b128 v[210:213], v165 offset:55296
	ds_read_b128 v[214:217], v165 offset:56320
	global_load_lds_dwordx4 v[190:191], off
	s_add_i32 m0, s10, 0x2000
	s_add_u32 s58, s58, 0x40080
	v_lshl_add_u64 v[190:191], v[218:219], 0, s[36:37]
	s_addc_u32 s59, s59, 0
	s_add_i32 s10, s11, s63
	global_load_lds_dwordx4 v[190:191], off
	s_mov_b32 m0, s10
	v_lshl_add_u64 v[190:191], s[58:59], 0, v[146:147]
	global_load_lds_dwordx4 v[190:191], off
	s_add_i32 m0, s10, 0x2000
	v_lshl_add_u64 v[190:191], s[58:59], 0, v[150:151]
	global_load_lds_dwordx4 v[190:191], off
	s_mov_b32 m0, s70
	v_lshl_add_u64 v[190:191], v[220:221], 0, s[36:37]
	global_load_lds_dwordx4 v[190:191], off
	s_mov_b32 m0, s71
	v_lshl_add_u64 v[190:191], v[222:223], 0, s[36:37]
	global_load_lds_dwordx4 v[190:191], off
	s_waitcnt vmcnt(8)
	s_waitcnt lgkmcnt(0)
	s_setprio 1
	s_barrier
	v_mfma_f32_16x16x32_bf16 v[60:63], v[128:131], v[182:185], v[60:63]
	v_mfma_f32_16x16x32_bf16 v[56:59], v[136:139], v[182:185], v[56:59]
	v_mfma_f32_16x16x32_bf16 v[48:51], v[128:131], v[194:197], v[48:51]
	v_mfma_f32_16x16x32_bf16 v[40:43], v[136:139], v[194:197], v[40:43]
	v_mfma_f32_16x16x32_bf16 v[32:35], v[128:131], v[202:205], v[32:35]
	v_mfma_f32_16x16x32_bf16 v[24:27], v[136:139], v[202:205], v[24:27]
	v_mfma_f32_16x16x32_bf16 v[16:19], v[128:131], v[210:213], v[16:19]
	v_mfma_f32_16x16x32_bf16 v[8:11], v[136:139], v[210:213], v[8:11]
	v_mfma_f32_16x16x32_bf16 v[60:63], v[132:135], v[186:189], v[60:63]
	v_mfma_f32_16x16x32_bf16 v[56:59], v[140:143], v[186:189], v[56:59]
	v_mfma_f32_16x16x32_bf16 v[48:51], v[132:135], v[198:201], v[48:51]
	v_mfma_f32_16x16x32_bf16 v[40:43], v[140:143], v[198:201], v[40:43]
	v_mfma_f32_16x16x32_bf16 v[32:35], v[132:135], v[206:209], v[32:35]
	v_mfma_f32_16x16x32_bf16 v[24:27], v[140:143], v[206:209], v[24:27]
	v_mfma_f32_16x16x32_bf16 v[16:19], v[132:135], v[214:217], v[16:19]
	v_mfma_f32_16x16x32_bf16 v[8:11], v[140:143], v[214:217], v[8:11]
	s_setprio 0
	s_setprio 1
	v_mfma_f32_16x16x32_bf16 v[52:55], v[166:169], v[182:185], v[52:55]
	v_mfma_f32_16x16x32_bf16 v[44:47], v[174:177], v[182:185], v[44:47]
	v_mfma_f32_16x16x32_bf16 v[36:39], v[166:169], v[194:197], v[36:39]
	v_mfma_f32_16x16x32_bf16 v[28:31], v[174:177], v[194:197], v[28:31]
	v_mfma_f32_16x16x32_bf16 v[20:23], v[166:169], v[202:205], v[20:23]
	v_mfma_f32_16x16x32_bf16 v[12:15], v[174:177], v[202:205], v[12:15]
	v_mfma_f32_16x16x32_bf16 v[4:7], v[166:169], v[210:213], v[4:7]
	v_mfma_f32_16x16x32_bf16 v[0:3], v[174:177], v[210:213], v[0:3]
	v_mfma_f32_16x16x32_bf16 v[52:55], v[170:173], v[186:189], v[52:55]
	v_mfma_f32_16x16x32_bf16 v[44:47], v[178:181], v[186:189], v[44:47]
	v_mfma_f32_16x16x32_bf16 v[36:39], v[170:173], v[198:201], v[36:39]
	v_mfma_f32_16x16x32_bf16 v[28:31], v[178:181], v[198:201], v[28:31]
	v_mfma_f32_16x16x32_bf16 v[20:23], v[170:173], v[206:209], v[20:23]
	v_mfma_f32_16x16x32_bf16 v[12:15], v[178:181], v[206:209], v[12:15]
	v_mfma_f32_16x16x32_bf16 v[4:7], v[170:173], v[214:217], v[4:7]
	v_mfma_f32_16x16x32_bf16 v[0:3], v[178:181], v[214:217], v[0:3]
	s_barrier
	s_setprio 0
	s_add_i32 s76, s76, 2
	s_add_u32 s56, s56, 0x100
	s_addc_u32 s57, s57, 0
	s_add_u32 s49, s49, 0x100
	s_addc_u32 s51, s51, 0
	s_cmp_gt_u32 s76, 13
	s_cbranch_scc0 .LBB0_200
	s_and_b64 vcc, exec, s[44:45]
	s_cbranch_vccz .LBB0_203
	s_barrier

; #define PG8_STAGE(bufoff, gbase, voff) do { _Pragma("unroll") for (int _i = 0; _i < 2; ++_i) \
;         __builtin_amdgcn_global_load_lds((const unsigned*)((const char*)(gbase) + (voff)[_i]), (PG8_LAS unsigned*)(lds + (bufoff) + ldsw + _i * 8192), 16, 0, 0); } while (0)
; #define PG8_LDA(dst, b, h) do { _Pragma("unroll") for (int m = 0; m < 4; ++m) _Pragma("unroll") for (int k = 0; k < 2; ++k) dst[m][k] = *(const PG8_LAS bf16x8*)(lds + PG8_SA(b, h) + aoff + m * 2048 + k * 1024); } while (0)
; #define PG8_LDB(dst, b, h) do { _Pragma("unroll") for (int n = 0; n < 2; ++n) _Pragma("unroll") for (int k = 0; k < 2; ++k) dst[n][k] = *(const PG8_LAS bf16x8*)(lds + PG8_SB(b, h) + boff + n * 2048 + k * 1024); } while (0)
; #define PG8_MMA(ai, bj, At, Bt) do { __builtin_amdgcn_s_setprio(1); _Pragma("unroll") for (int m = 0; m < 4; ++m) _Pragma("unroll") for (int n = 0; n < 2; ++n) _Pragma("unroll") for (int k = 0; k < 2; ++k) \
;         acc[ai][bj][m][n] = __builtin_amdgcn_mfma_f32_16x16x32_bf16(Bt[n][k], At[m][k], acc[ai][bj][m][n], 0, 0, 0); __builtin_amdgcn_s_setprio(0); } while (0)
; #define PG8_WAIT_V(n) asm volatile("s_waitcnt vmcnt(" #n ")" ::: "memory")
; #define PG8_WAIT_L(n) asm volatile("s_waitcnt lgkmcnt(" #n ")" ::: "memory")
; template <class Epi, class Sched, bool ALIGN_EPI = false, bool SP2 = false>
; __device__ __forceinline__ void gemm_phase(PG8_LAS unsigned char* lds, const Gemm g, const Sched& S, const Epi& E) {
;     ...
;             const bool last = (t == nt - 2);
;             const char* a1 = cA + (size_t)(t + 1) * kstep;
;             const char* a2 = last ? nA : cA + (size_t)(t + 2) * kstep; const char* b2 = last ? nB : cB + (size_t)(t + 2) * kstep;
;             const char* a3 = a2 + kstep; const char* b3 = b2 + kstep;
;             if (last && has_next) S.a_ready(nxt);
;             if constexpr (SP2) {
;             PG8_LDB(B0, 0, 0); PG8_LDB(B1, 0, 1); PG8_SCHED; PG8_LDA(At, 0, 0); PG8_STAGE(PG8_SA(1, 1), a1 + hstep, voffA);
;             PG8_WAIT_V(8); PG8_WAIT_L(0); PG8_BAR; PG8_MMA(0, 0, At, B0); PG8_MMA(0, 1, At, B1); PG8_BAR; PG8_SCHED;
;             PG8_LDA(At, 0, 1); PG8_STAGE(PG8_SB(0, 0), b2, voffB); PG8_STAGE(PG8_SB(0, 1), b2 + hstep, voffB); PG8_STAGE(PG8_SA(0, 0), a2, voffA);
;             PG8_WAIT_V(8); PG8_WAIT_L(0); PG8_BAR; PG8_MMA(1, 0, At, B0); PG8_MMA(1, 1, At, B1); PG8_BAR; PG8_SCHED;
.LBB0_488:
	s_add_u32 s10, s34, 0xfffc0080
	s_addc_u32 s11, s35, -1
	s_add_i32 s77, 0, 0x10000
	s_cmp_eq_u32 s76, 4
	s_cselect_b32 s53, s45, s11
	s_cselect_b32 s52, s44, s10
	s_cselect_b32 s51, s49, s75
	s_cselect_b32 s50, s48, s19
	s_add_i32 s78, 0, 0x14000
	v_add_u32_e32 v140, s77, v246
	v_add_u32_e32 v156, s77, v246
	v_add_u32_e32 v156, 0x1000, v156
	ds_read_b128 v[128:131], v140
	ds_read_b128 v[132:135], v140 offset:1024
	ds_read_b128 v[136:139], v140 offset:2048
	ds_read_b128 v[140:143], v140 offset:3072
	ds_read_b128 v[144:147], v156
	ds_read_b128 v[148:151], v156 offset:1024
	ds_read_b128 v[152:155], v156 offset:2048
	ds_read_b128 v[156:159], v156 offset:3072
	v_lshl_add_u64 v[208:209], s[34:35], 0, v[204:205]
	s_add_i32 m0, s55, 0xc000
	ds_read_b128 v[160:163], v249
	ds_read_b128 v[164:167], v249 offset:1024
	ds_read_b128 v[168:171], v249 offset:2048
	ds_read_b128 v[172:175], v249 offset:3072
	ds_read_b128 v[176:179], v249 offset:4096
	ds_read_b128 v[180:183], v249 offset:5120
	ds_read_b128 v[184:187], v249 offset:6144
	ds_read_b128 v[188:191], v249 offset:7168
	global_load_lds_dwordx4 v[208:209], off
	s_add_i32 m0, s55, 0xe000
	v_lshl_add_u64 v[208:209], s[34:35], 0, v[206:207]
	global_load_lds_dwordx4 v[208:209], off
	s_waitcnt vmcnt(8)
	s_waitcnt lgkmcnt(0)
	s_setprio 1
	s_barrier
	v_mfma_f32_16x16x32_bf16 v[124:127], v[128:131], v[160:163], v[124:127]
	v_mfma_f32_16x16x32_bf16 v[120:123], v[136:139], v[160:163], v[120:123]
	v_mfma_f32_16x16x32_bf16 v[116:119], v[128:131], v[168:171], v[116:119]
	v_mfma_f32_16x16x32_bf16 v[112:115], v[136:139], v[168:171], v[112:115]
	v_mfma_f32_16x16x32_bf16 v[108:111], v[128:131], v[176:179], v[108:111]
	v_mfma_f32_16x16x32_bf16 v[104:107], v[136:139], v[176:179], v[104:107]
	v_mfma_f32_16x16x32_bf16 v[100:103], v[128:131], v[184:187], v[100:103]
	v_mfma_f32_16x16x32_bf16 v[96:99], v[136:139], v[184:187], v[96:99]
	v_mfma_f32_16x16x32_bf16 v[124:127], v[132:135], v[164:167], v[124:127]
	v_mfma_f32_16x16x32_bf16 v[120:123], v[140:143], v[164:167], v[120:123]
	v_mfma_f32_16x16x32_bf16 v[116:119], v[132:135], v[172:175], v[116:119]
	v_mfma_f32_16x16x32_bf16 v[112:115], v[140:143], v[172:175], v[112:115]
	v_mfma_f32_16x16x32_bf16 v[108:111], v[132:135], v[180:183], v[108:111]
	v_mfma_f32_16x16x32_bf16 v[104:107], v[140:143], v[180:183], v[104:107]
	v_mfma_f32_16x16x32_bf16 v[100:103], v[132:135], v[188:191], v[100:103]
	v_mfma_f32_16x16x32_bf16 v[96:99], v[140:143], v[188:191], v[96:99]
	s_setprio 0
	s_setprio 1
	v_mfma_f32_16x16x32_bf16 v[92:95], v[144:147], v[160:163], v[92:95]
	v_mfma_f32_16x16x32_bf16 v[88:91], v[152:155], v[160:163], v[88:91]
	v_mfma_f32_16x16x32_bf16 v[84:87], v[144:147], v[168:171], v[84:87]
	v_mfma_f32_16x16x32_bf16 v[80:83], v[152:155], v[168:171], v[80:83]
	v_mfma_f32_16x16x32_bf16 v[76:79], v[144:147], v[176:179], v[76:79]
	v_mfma_f32_16x16x32_bf16 v[72:75], v[152:155], v[176:179], v[72:75]
	v_mfma_f32_16x16x32_bf16 v[68:71], v[144:147], v[184:187], v[68:71]
	v_mfma_f32_16x16x32_bf16 v[64:67], v[152:155], v[184:187], v[64:67]
	v_mfma_f32_16x16x32_bf16 v[92:95], v[148:151], v[164:167], v[92:95]
	v_mfma_f32_16x16x32_bf16 v[88:91], v[156:159], v[164:167], v[88:91]
	v_mfma_f32_16x16x32_bf16 v[84:87], v[148:151], v[172:175], v[84:87]
	v_mfma_f32_16x16x32_bf16 v[80:83], v[156:159], v[172:175], v[80:83]
	v_mfma_f32_16x16x32_bf16 v[76:79], v[148:151], v[180:183], v[76:79]
	v_mfma_f32_16x16x32_bf16 v[72:75], v[156:159], v[180:183], v[72:75]
	v_mfma_f32_16x16x32_bf16 v[68:71], v[148:151], v[188:191], v[68:71]
	v_mfma_f32_16x16x32_bf16 v[64:67], v[156:159], v[188:191], v[64:67]
	s_barrier
	s_setprio 0
	s_add_i32 s10, s77, s14
	v_lshl_add_u64 v[208:209], s[50:51], 0, v[198:199]
	s_mov_b32 m0, s10
	ds_read_b128 v[160:163], v249 offset:16384
	ds_read_b128 v[164:167], v249 offset:17408
	ds_read_b128 v[168:171], v249 offset:18432
	ds_read_b128 v[172:175], v249 offset:19456
	ds_read_b128 v[176:179], v249 offset:20480
	ds_read_b128 v[180:183], v249 offset:21504
	ds_read_b128 v[184:187], v249 offset:22528
	ds_read_b128 v[188:191], v249 offset:23552
	global_load_lds_dwordx4 v[208:209], off
	s_add_i32 m0, s10, 0x2000
	s_add_u32 s10, s50, 0x40000
	v_lshl_add_u64 v[210:211], s[50:51], 0, v[194:195]
	s_addc_u32 s11, s51, 0
	s_add_i32 s77, s78, s14
	global_load_lds_dwordx4 v[210:211], off
	v_lshl_add_u64 v[212:213], s[10:11], 0, v[198:199]
	s_mov_b32 m0, s77
	v_lshl_add_u64 v[214:215], s[52:53], 0, v[196:197]
	global_load_lds_dwordx4 v[212:213], off
	s_add_i32 m0, s77, 0x2000
	v_lshl_add_u64 v[212:213], s[10:11], 0, v[194:195]
	global_load_lds_dwordx4 v[212:213], off
	s_mov_b32 m0, s55
	v_lshl_add_u64 v[212:213], s[52:53], 0, v[200:201]
	global_load_lds_dwordx4 v[212:213], off
	s_mov_b32 m0, s58
	s_nop 0
	global_load_lds_dwordx4 v[214:215], off
	s_waitcnt vmcnt(8)
	s_waitcnt lgkmcnt(0)
	s_setprio 1
	s_barrier
; #define PG8_STAGE(bufoff, gbase, voff) do { _Pragma("unroll") for (int _i = 0; _i < 2; ++_i) \
;         __builtin_amdgcn_global_load_lds((const unsigned*)((const char*)(gbase) + (voff)[_i]), (PG8_LAS unsigned*)(lds + (bufoff) + ldsw + _i * 8192), 16, 0, 0); } while (0)
; #define PG8_LDA(dst, b, h) do { _Pragma("unroll") for (int m = 0; m < 4; ++m) _Pragma("unroll") for (int k = 0; k < 2; ++k) dst[m][k] = *(const PG8_LAS bf16x8*)(lds + PG8_SA(b, h) + aoff + m * 2048 + k * 1024); } while (0)
; #define PG8_LDB(dst, b, h) do { _Pragma("unroll") for (int n = 0; n < 2; ++n) _Pragma("unroll") for (int k = 0; k < 2; ++k) dst[n][k] = *(const PG8_LAS bf16x8*)(lds + PG8_SB(b, h) + boff + n * 2048 + k * 1024); } while (0)
; #define PG8_MMA(ai, bj, At, Bt) do { __builtin_amdgcn_s_setprio(1); _Pragma("unroll") for (int m = 0; m < 4; ++m) _Pragma("unroll") for (int n = 0; n < 2; ++n) _Pragma("unroll") for (int k = 0; k < 2; ++k) \
;         acc[ai][bj][m][n] = __builtin_amdgcn_mfma_f32_16x16x32_bf16(Bt[n][k], At[m][k], acc[ai][bj][m][n], 0, 0, 0); __builtin_amdgcn_s_setprio(0); } while (0)
; #define PG8_WAIT_V(n) asm volatile("s_waitcnt vmcnt(" #n ")" ::: "memory")
; #define PG8_WAIT_L(n) asm volatile("s_waitcnt lgkmcnt(" #n ")" ::: "memory")
; #define PG8_BAR __builtin_amdgcn_s_barrier()
; #define PG8_SCHED __builtin_amdgcn_sched_barrier(0)
; template <class Epi, class Sched, bool ALIGN_EPI = false, bool SP2 = false>
; __device__ __forceinline__ void gemm_phase(PG8_LAS unsigned char* lds, const Gemm g, const Sched& S, const Epi& E) {
;     ...
;             PG8_WAIT_V(8); PG8_WAIT_L(0); PG8_BAR; PG8_MMA(1, 0, At, B0); PG8_MMA(1, 1, At, B1); PG8_BAR; PG8_SCHED;
;             PG8_LDB(B0, 1, 0); PG8_LDB(B1, 1, 1); PG8_SCHED; PG8_LDA(At, 1, 0); PG8_STAGE(PG8_SA(0, 1), a2 + hstep, voffA);
;             PG8_WAIT_V(8); PG8_WAIT_L(0); PG8_BAR; PG8_MMA(0, 0, At, B0); PG8_MMA(0, 1, At, B1); PG8_BAR; PG8_SCHED;
	v_mfma_f32_16x16x32_bf16 v[60:63], v[128:131], v[160:163], v[60:63]
	v_mfma_f32_16x16x32_bf16 v[56:59], v[136:139], v[160:163], v[56:59]
	v_mfma_f32_16x16x32_bf16 v[52:55], v[128:131], v[168:171], v[52:55]
	v_mfma_f32_16x16x32_bf16 v[48:51], v[136:139], v[168:171], v[48:51]
	v_mfma_f32_16x16x32_bf16 v[44:47], v[128:131], v[176:179], v[44:47]
	v_mfma_f32_16x16x32_bf16 v[40:43], v[136:139], v[176:179], v[40:43]
	v_mfma_f32_16x16x32_bf16 v[36:39], v[128:131], v[184:187], v[36:39]
	v_mfma_f32_16x16x32_bf16 v[32:35], v[136:139], v[184:187], v[32:35]
	v_mfma_f32_16x16x32_bf16 v[60:63], v[132:135], v[164:167], v[60:63]
	v_mfma_f32_16x16x32_bf16 v[56:59], v[140:143], v[164:167], v[56:59]
	v_mfma_f32_16x16x32_bf16 v[52:55], v[132:135], v[172:175], v[52:55]
	v_mfma_f32_16x16x32_bf16 v[48:51], v[140:143], v[172:175], v[48:51]
	v_mfma_f32_16x16x32_bf16 v[44:47], v[132:135], v[180:183], v[44:47]
	v_mfma_f32_16x16x32_bf16 v[40:43], v[140:143], v[180:183], v[40:43]
	v_mfma_f32_16x16x32_bf16 v[36:39], v[132:135], v[188:191], v[36:39]
	v_mfma_f32_16x16x32_bf16 v[32:35], v[140:143], v[188:191], v[32:35]
	s_setprio 0
	s_setprio 1
	v_mfma_f32_16x16x32_bf16 v[28:31], v[144:147], v[160:163], v[28:31]
	v_mfma_f32_16x16x32_bf16 v[24:27], v[152:155], v[160:163], v[24:27]
	v_mfma_f32_16x16x32_bf16 v[20:23], v[144:147], v[168:171], v[20:23]
	v_mfma_f32_16x16x32_bf16 v[16:19], v[152:155], v[168:171], v[16:19]
	v_mfma_f32_16x16x32_bf16 v[12:15], v[144:147], v[176:179], v[12:15]
	v_mfma_f32_16x16x32_bf16 v[8:11], v[152:155], v[176:179], v[8:11]
	v_mfma_f32_16x16x32_bf16 v[4:7], v[144:147], v[184:187], v[4:7]
	v_mfma_f32_16x16x32_bf16 v[0:3], v[152:155], v[184:187], v[0:3]
	v_mfma_f32_16x16x32_bf16 v[28:31], v[148:151], v[164:167], v[28:31]
	v_mfma_f32_16x16x32_bf16 v[24:27], v[156:159], v[164:167], v[24:27]
	v_mfma_f32_16x16x32_bf16 v[20:23], v[148:151], v[172:175], v[20:23]
	v_mfma_f32_16x16x32_bf16 v[16:19], v[156:159], v[172:175], v[16:19]
	v_mfma_f32_16x16x32_bf16 v[12:15], v[148:151], v[180:183], v[12:15]
	v_mfma_f32_16x16x32_bf16 v[8:11], v[156:159], v[180:183], v[8:11]
	v_mfma_f32_16x16x32_bf16 v[4:7], v[148:151], v[188:191], v[4:7]
	v_mfma_f32_16x16x32_bf16 v[0:3], v[156:159], v[188:191], v[0:3]
	s_barrier
	s_setprio 0
	s_add_i32 s77, 0, 0x18000
	s_add_i32 s78, 0, 0x1c000
	v_add_u32_e32 v140, s77, v246
	v_add_u32_e32 v156, s77, v246
	v_add_u32_e32 v156, 0x1000, v156
	ds_read_b128 v[128:131], v140
	ds_read_b128 v[132:135], v140 offset:1024
	ds_read_b128 v[136:139], v140 offset:2048
	ds_read_b128 v[140:143], v140 offset:3072
	ds_read_b128 v[144:147], v156
	ds_read_b128 v[148:151], v156 offset:1024
	ds_read_b128 v[152:155], v156 offset:2048
	ds_read_b128 v[156:159], v156 offset:3072
	s_add_u32 s10, s52, 0x40000
	s_addc_u32 s11, s53, 0
	s_mov_b32 m0, s59
	v_lshl_add_u64 v[216:217], s[10:11], 0, v[200:201]
	ds_read_b128 v[160:163], v249 offset:32768
	ds_read_b128 v[164:167], v249 offset:33792
	ds_read_b128 v[168:171], v249 offset:34816
	ds_read_b128 v[172:175], v249 offset:35840
	ds_read_b128 v[176:179], v249 offset:36864
	ds_read_b128 v[180:183], v249 offset:37888
	ds_read_b128 v[184:187], v249 offset:38912
	ds_read_b128 v[188:191], v249 offset:39936
	global_load_lds_dwordx4 v[216:217], off
	s_mov_b32 m0, s60
	v_lshl_add_u64 v[216:217], s[10:11], 0, v[196:197]
	global_load_lds_dwordx4 v[216:217], off
	s_waitcnt vmcnt(8)
	s_waitcnt lgkmcnt(0)
	s_setprio 1
	s_barrier
	v_mfma_f32_16x16x32_bf16 v[124:127], v[128:131], v[160:163], v[124:127]
	v_mfma_f32_16x16x32_bf16 v[120:123], v[136:139], v[160:163], v[120:123]
	v_mfma_f32_16x16x32_bf16 v[116:119], v[128:131], v[168:171], v[116:119]
	v_mfma_f32_16x16x32_bf16 v[112:115], v[136:139], v[168:171], v[112:115]
	v_mfma_f32_16x16x32_bf16 v[108:111], v[128:131], v[176:179], v[108:111]
	v_mfma_f32_16x16x32_bf16 v[104:107], v[136:139], v[176:179], v[104:107]
	v_mfma_f32_16x16x32_bf16 v[100:103], v[128:131], v[184:187], v[100:103]
	v_mfma_f32_16x16x32_bf16 v[96:99], v[136:139], v[184:187], v[96:99]
	v_mfma_f32_16x16x32_bf16 v[124:127], v[132:135], v[164:167], v[124:127]
	v_mfma_f32_16x16x32_bf16 v[120:123], v[140:143], v[164:167], v[120:123]
	v_mfma_f32_16x16x32_bf16 v[116:119], v[132:135], v[172:175], v[116:119]
	v_mfma_f32_16x16x32_bf16 v[112:115], v[140:143], v[172:175], v[112:115]
	v_mfma_f32_16x16x32_bf16 v[108:111], v[132:135], v[180:183], v[108:111]
	v_mfma_f32_16x16x32_bf16 v[104:107], v[140:143], v[180:183], v[104:107]
	v_mfma_f32_16x16x32_bf16 v[100:103], v[132:135], v[188:191], v[100:103]
	v_mfma_f32_16x16x32_bf16 v[96:99], v[140:143], v[188:191], v[96:99]
	s_setprio 0
	s_setprio 1
	v_mfma_f32_16x16x32_bf16 v[92:95], v[144:147], v[160:163], v[92:95]
	v_mfma_f32_16x16x32_bf16 v[88:91], v[152:155], v[160:163], v[88:91]
	v_mfma_f32_16x16x32_bf16 v[84:87], v[144:147], v[168:171], v[84:87]
	v_mfma_f32_16x16x32_bf16 v[80:83], v[152:155], v[168:171], v[80:83]
	v_mfma_f32_16x16x32_bf16 v[76:79], v[144:147], v[176:179], v[76:79]
	v_mfma_f32_16x16x32_bf16 v[72:75], v[152:155], v[176:179], v[72:75]
	v_mfma_f32_16x16x32_bf16 v[68:71], v[144:147], v[184:187], v[68:71]
	v_mfma_f32_16x16x32_bf16 v[64:67], v[152:155], v[184:187], v[64:67]
	v_mfma_f32_16x16x32_bf16 v[92:95], v[148:151], v[164:167], v[92:95]
	v_mfma_f32_16x16x32_bf16 v[88:91], v[156:159], v[164:167], v[88:91]
	v_mfma_f32_16x16x32_bf16 v[84:87], v[148:151], v[172:175], v[84:87]
	v_mfma_f32_16x16x32_bf16 v[80:83], v[156:159], v[172:175], v[80:83]
	v_mfma_f32_16x16x32_bf16 v[76:79], v[148:151], v[180:183], v[76:79]
	v_mfma_f32_16x16x32_bf16 v[72:75], v[156:159], v[180:183], v[72:75]
	v_mfma_f32_16x16x32_bf16 v[68:71], v[148:151], v[188:191], v[68:71]
	v_mfma_f32_16x16x32_bf16 v[64:67], v[156:159], v[188:191], v[64:67]
	s_barrier
; #define PG8_STAGE(bufoff, gbase, voff) do { _Pragma("unroll") for (int _i = 0; _i < 2; ++_i) \
;         __builtin_amdgcn_global_load_lds((const unsigned*)((const char*)(gbase) + (voff)[_i]), (PG8_LAS unsigned*)(lds + (bufoff) + ldsw + _i * 8192), 16, 0, 0); } while (0)
; #define PG8_LDA(dst, b, h) do { _Pragma("unroll") for (int m = 0; m < 4; ++m) _Pragma("unroll") for (int k = 0; k < 2; ++k) dst[m][k] = *(const PG8_LAS bf16x8*)(lds + PG8_SA(b, h) + aoff + m * 2048 + k * 1024); } while (0)
; #define PG8_MMA(ai, bj, At, Bt) do { __builtin_amdgcn_s_setprio(1); _Pragma("unroll") for (int m = 0; m < 4; ++m) _Pragma("unroll") for (int n = 0; n < 2; ++n) _Pragma("unroll") for (int k = 0; k < 2; ++k) \
;         acc[ai][bj][m][n] = __builtin_amdgcn_mfma_f32_16x16x32_bf16(Bt[n][k], At[m][k], acc[ai][bj][m][n], 0, 0, 0); __builtin_amdgcn_s_setprio(0); } while (0)
; #define PG8_WAIT_V(n) asm volatile("s_waitcnt vmcnt(" #n ")" ::: "memory")
; #define PG8_WAIT_L(n) asm volatile("s_waitcnt lgkmcnt(" #n ")" ::: "memory")
; #define PG8_BAR __builtin_amdgcn_s_barrier()
; #define PG8_SCHED __builtin_amdgcn_sched_barrier(0)
; template <class Epi, class Sched, bool ALIGN_EPI = false, bool SP2 = false>
; __device__ __forceinline__ void gemm_phase(PG8_LAS unsigned char* lds, const Gemm g, const Sched& S, const Epi& E) {
;     ...
;             PG8_LDA(At, 1, 1); PG8_STAGE(PG8_SB(1, 0), b3, voffB); PG8_STAGE(PG8_SB(1, 1), b3 + hstep, voffB); PG8_STAGE(PG8_SA(1, 0), a3, voffA);
;             PG8_WAIT_V(8); PG8_WAIT_L(0); PG8_BAR; PG8_MMA(1, 0, At, B0); PG8_MMA(1, 1, At, B1); PG8_BAR; PG8_SCHED;
;     ...
;         if constexpr (ALIGN_EPI) { if (wr == 0) PG8_BAR; }
	s_setprio 0
	s_add_i32 s10, s77, s14
	v_lshl_add_u64 v[208:209], v[208:209], 0, s[36:37]
	s_mov_b32 m0, s10
	ds_read_b128 v[160:163], v249 offset:49152
	ds_read_b128 v[164:167], v249 offset:50176
	ds_read_b128 v[168:171], v249 offset:51200
	ds_read_b128 v[172:175], v249 offset:52224
	ds_read_b128 v[176:179], v249 offset:53248
	ds_read_b128 v[180:183], v249 offset:54272
	ds_read_b128 v[184:187], v249 offset:55296
	ds_read_b128 v[188:191], v249 offset:56320
	global_load_lds_dwordx4 v[208:209], off
	s_add_i32 m0, s10, 0x2000
	s_add_u32 s10, s50, 0x40080
	v_lshl_add_u64 v[208:209], v[210:211], 0, s[36:37]
	s_addc_u32 s11, s51, 0
	s_add_i32 s50, s78, s14
	global_load_lds_dwordx4 v[208:209], off
	s_mov_b32 m0, s50
	v_lshl_add_u64 v[208:209], s[10:11], 0, v[198:199]
	global_load_lds_dwordx4 v[208:209], off
	s_add_i32 m0, s50, 0x2000
	v_lshl_add_u64 v[208:209], s[10:11], 0, v[194:195]
	global_load_lds_dwordx4 v[208:209], off
	s_mov_b32 m0, s65
	v_lshl_add_u64 v[208:209], v[212:213], 0, s[36:37]
	global_load_lds_dwordx4 v[208:209], off
	s_mov_b32 m0, s66
	v_lshl_add_u64 v[208:209], v[214:215], 0, s[36:37]
	global_load_lds_dwordx4 v[208:209], off
	s_waitcnt vmcnt(8)
	s_waitcnt lgkmcnt(0)
	s_setprio 1
	s_barrier
	v_mfma_f32_16x16x32_bf16 v[60:63], v[128:131], v[160:163], v[60:63]
	v_mfma_f32_16x16x32_bf16 v[56:59], v[136:139], v[160:163], v[56:59]
	v_mfma_f32_16x16x32_bf16 v[52:55], v[128:131], v[168:171], v[52:55]
	v_mfma_f32_16x16x32_bf16 v[48:51], v[136:139], v[168:171], v[48:51]
	v_mfma_f32_16x16x32_bf16 v[44:47], v[128:131], v[176:179], v[44:47]
	v_mfma_f32_16x16x32_bf16 v[40:43], v[136:139], v[176:179], v[40:43]
	v_mfma_f32_16x16x32_bf16 v[36:39], v[128:131], v[184:187], v[36:39]
	v_mfma_f32_16x16x32_bf16 v[32:35], v[136:139], v[184:187], v[32:35]
	v_mfma_f32_16x16x32_bf16 v[60:63], v[132:135], v[164:167], v[60:63]
	v_mfma_f32_16x16x32_bf16 v[56:59], v[140:143], v[164:167], v[56:59]
	v_mfma_f32_16x16x32_bf16 v[52:55], v[132:135], v[172:175], v[52:55]
	v_mfma_f32_16x16x32_bf16 v[48:51], v[140:143], v[172:175], v[48:51]
	v_mfma_f32_16x16x32_bf16 v[44:47], v[132:135], v[180:183], v[44:47]
	v_mfma_f32_16x16x32_bf16 v[40:43], v[140:143], v[180:183], v[40:43]
	v_mfma_f32_16x16x32_bf16 v[36:39], v[132:135], v[188:191], v[36:39]
	v_mfma_f32_16x16x32_bf16 v[32:35], v[140:143], v[188:191], v[32:35]
	s_setprio 0
	s_setprio 1
	v_mfma_f32_16x16x32_bf16 v[28:31], v[144:147], v[160:163], v[28:31]
	v_mfma_f32_16x16x32_bf16 v[24:27], v[152:155], v[160:163], v[24:27]
	v_mfma_f32_16x16x32_bf16 v[20:23], v[144:147], v[168:171], v[20:23]
	v_mfma_f32_16x16x32_bf16 v[16:19], v[152:155], v[168:171], v[16:19]
	v_mfma_f32_16x16x32_bf16 v[12:15], v[144:147], v[176:179], v[12:15]
	v_mfma_f32_16x16x32_bf16 v[8:11], v[152:155], v[176:179], v[8:11]
	v_mfma_f32_16x16x32_bf16 v[4:7], v[144:147], v[184:187], v[4:7]
	v_mfma_f32_16x16x32_bf16 v[0:3], v[152:155], v[184:187], v[0:3]
	v_mfma_f32_16x16x32_bf16 v[28:31], v[148:151], v[164:167], v[28:31]
	v_mfma_f32_16x16x32_bf16 v[24:27], v[156:159], v[164:167], v[24:27]
	v_mfma_f32_16x16x32_bf16 v[20:23], v[148:151], v[172:175], v[20:23]
	v_mfma_f32_16x16x32_bf16 v[16:19], v[156:159], v[172:175], v[16:19]
	v_mfma_f32_16x16x32_bf16 v[12:15], v[148:151], v[180:183], v[12:15]
	v_mfma_f32_16x16x32_bf16 v[8:11], v[156:159], v[180:183], v[8:11]
	v_mfma_f32_16x16x32_bf16 v[4:7], v[148:151], v[188:191], v[4:7]
	v_mfma_f32_16x16x32_bf16 v[0:3], v[156:159], v[188:191], v[0:3]
	s_barrier
	s_setprio 0
	s_add_i32 s76, s76, 2
	s_add_u32 s34, s34, 0x100
	s_addc_u32 s35, s35, 0
	s_add_u32 s19, s19, 0x100
	s_addc_u32 s75, s75, 0
	s_cmp_gt_u32 s76, 5
	s_cbranch_scc0 .LBB0_488
	s_and_b64 vcc, exec, s[24:25]
	s_cbranch_vccz .LBB0_491
	s_barrier

; #define PG8_STAGE(bufoff, gbase, voff) do { _Pragma("unroll") for (int _i = 0; _i < 2; ++_i) \
;         __builtin_amdgcn_global_load_lds((const unsigned*)((const char*)(gbase) + (voff)[_i]), (PG8_LAS unsigned*)(lds + (bufoff) + ldsw + _i * 8192), 16, 0, 0); } while (0)
; #define PG8_LDA(dst, b, h) do { _Pragma("unroll") for (int m = 0; m < 4; ++m) _Pragma("unroll") for (int k = 0; k < 2; ++k) dst[m][k] = *(const PG8_LAS bf16x8*)(lds + PG8_SA(b, h) + aoff + m * 2048 + k * 1024); } while (0)
; #define PG8_LDB(dst, b, h) do { _Pragma("unroll") for (int n = 0; n < 2; ++n) _Pragma("unroll") for (int k = 0; k < 2; ++k) dst[n][k] = *(const PG8_LAS bf16x8*)(lds + PG8_SB(b, h) + boff + n * 2048 + k * 1024); } while (0)
; #define PG8_MMA(ai, bj, At, Bt) do { __builtin_amdgcn_s_setprio(1); _Pragma("unroll") for (int m = 0; m < 4; ++m) _Pragma("unroll") for (int n = 0; n < 2; ++n) _Pragma("unroll") for (int k = 0; k < 2; ++k) \
;         acc[ai][bj][m][n] = __builtin_amdgcn_mfma_f32_16x16x32_bf16(Bt[n][k], At[m][k], acc[ai][bj][m][n], 0, 0, 0); __builtin_amdgcn_s_setprio(0); } while (0)
; #define PG8_WAIT_V(n) asm volatile("s_waitcnt vmcnt(" #n ")" ::: "memory")
; #define PG8_WAIT_L(n) asm volatile("s_waitcnt lgkmcnt(" #n ")" ::: "memory")
; template <class Epi, class Sched, bool ALIGN_EPI = false, bool SP2 = false>
; __device__ __forceinline__ void gemm_phase(PG8_LAS unsigned char* lds, const Gemm g, const Sched& S, const Epi& E) {
;     ...
;             const bool last = (t == nt - 2);
;             const char* a1 = cA + (size_t)(t + 1) * kstep;
;             const char* a2 = last ? nA : cA + (size_t)(t + 2) * kstep; const char* b2 = last ? nB : cB + (size_t)(t + 2) * kstep;
;             const char* a3 = a2 + kstep; const char* b3 = b2 + kstep;
;             if (last && has_next) S.a_ready(nxt);
;             if constexpr (SP2) {
;             PG8_LDB(B0, 0, 0); PG8_LDB(B1, 0, 1); PG8_SCHED; PG8_LDA(At, 0, 0); PG8_STAGE(PG8_SA(1, 1), a1 + hstep, voffA);
;             PG8_WAIT_V(8); PG8_WAIT_L(0); PG8_BAR; PG8_MMA(0, 0, At, B0); PG8_MMA(0, 1, At, B1); PG8_BAR; PG8_SCHED;
;             PG8_LDA(At, 0, 1); PG8_STAGE(PG8_SB(0, 0), b2, voffB); PG8_STAGE(PG8_SB(0, 1), b2 + hstep, voffB); PG8_STAGE(PG8_SA(0, 0), a2, voffA);
;             PG8_WAIT_V(8); PG8_WAIT_L(0); PG8_BAR; PG8_MMA(1, 0, At, B0); PG8_MMA(1, 1, At, B1); PG8_BAR; PG8_SCHED;
.LBB0_577:
	s_add_u32 s10, s44, 0xfffc0080
	s_addc_u32 s11, s45, -1
	s_add_i32 s64, 0, 0x10000
	s_cmp_eq_u32 s63, 12
	s_cselect_b32 s49, s29, s11
	s_cselect_b32 s48, s43, s10
	v_add_u32_e32 v146, s64, v149
	s_cselect_b32 s47, s27, s62
	s_cselect_b32 s46, s60, s61
	s_add_i32 s65, 0, 0x14000
	ds_read_b128 v[128:131], v146
	ds_read_b128 v[154:157], v146 offset:1024
	ds_read_b128 v[158:161], v146 offset:2048
	ds_read_b128 v[162:165], v146 offset:3072
	v_add_u32_e32 v146, s65, v149
	ds_read_b128 v[166:169], v146
	ds_read_b128 v[170:173], v146 offset:1024
	ds_read_b128 v[174:177], v146 offset:2048
	ds_read_b128 v[178:181], v146 offset:3072
	v_lshl_add_u64 v[190:191], s[44:45], 0, v[142:143]
	s_add_i32 m0, s51, 0xc000
	ds_read_b128 v[182:185], v153
	ds_read_b128 v[186:189], v153 offset:1024
	ds_read_b128 v[194:197], v153 offset:2048
	ds_read_b128 v[198:201], v153 offset:3072
	ds_read_b128 v[202:205], v153 offset:4096
	ds_read_b128 v[206:209], v153 offset:5120
	ds_read_b128 v[210:213], v153 offset:6144
	ds_read_b128 v[214:217], v153 offset:7168
	global_load_lds_dwordx4 v[190:191], off
	s_add_i32 m0, s51, 0xe000
	v_lshl_add_u64 v[190:191], s[44:45], 0, v[144:145]
	global_load_lds_dwordx4 v[190:191], off
	s_waitcnt vmcnt(8)
	s_waitcnt lgkmcnt(0)
	s_setprio 1
	s_barrier
	v_mfma_f32_16x16x32_bf16 v[124:127], v[128:131], v[182:185], v[124:127]
	v_mfma_f32_16x16x32_bf16 v[116:119], v[158:161], v[182:185], v[116:119]
	v_mfma_f32_16x16x32_bf16 v[108:111], v[128:131], v[194:197], v[108:111]
	v_mfma_f32_16x16x32_bf16 v[100:103], v[158:161], v[194:197], v[100:103]
	v_mfma_f32_16x16x32_bf16 v[92:95], v[128:131], v[202:205], v[92:95]
	v_mfma_f32_16x16x32_bf16 v[84:87], v[158:161], v[202:205], v[84:87]
	v_mfma_f32_16x16x32_bf16 v[76:79], v[128:131], v[210:213], v[76:79]
	v_mfma_f32_16x16x32_bf16 v[68:71], v[158:161], v[210:213], v[68:71]
	v_mfma_f32_16x16x32_bf16 v[124:127], v[154:157], v[186:189], v[124:127]
	v_mfma_f32_16x16x32_bf16 v[116:119], v[162:165], v[186:189], v[116:119]
	v_mfma_f32_16x16x32_bf16 v[108:111], v[154:157], v[198:201], v[108:111]
	v_mfma_f32_16x16x32_bf16 v[100:103], v[162:165], v[198:201], v[100:103]
	v_mfma_f32_16x16x32_bf16 v[92:95], v[154:157], v[206:209], v[92:95]
	v_mfma_f32_16x16x32_bf16 v[84:87], v[162:165], v[206:209], v[84:87]
	v_mfma_f32_16x16x32_bf16 v[76:79], v[154:157], v[214:217], v[76:79]
	v_mfma_f32_16x16x32_bf16 v[68:71], v[162:165], v[214:217], v[68:71]
	s_setprio 0
	s_setprio 1
	v_mfma_f32_16x16x32_bf16 v[120:123], v[166:169], v[182:185], v[120:123]
	v_mfma_f32_16x16x32_bf16 v[112:115], v[174:177], v[182:185], v[112:115]
	v_mfma_f32_16x16x32_bf16 v[104:107], v[166:169], v[194:197], v[104:107]
	v_mfma_f32_16x16x32_bf16 v[96:99], v[174:177], v[194:197], v[96:99]
	v_mfma_f32_16x16x32_bf16 v[88:91], v[166:169], v[202:205], v[88:91]
	v_mfma_f32_16x16x32_bf16 v[80:83], v[174:177], v[202:205], v[80:83]
	v_mfma_f32_16x16x32_bf16 v[72:75], v[166:169], v[210:213], v[72:75]
	v_mfma_f32_16x16x32_bf16 v[64:67], v[174:177], v[210:213], v[64:67]
	v_mfma_f32_16x16x32_bf16 v[120:123], v[170:173], v[186:189], v[120:123]
	v_mfma_f32_16x16x32_bf16 v[112:115], v[178:181], v[186:189], v[112:115]
	v_mfma_f32_16x16x32_bf16 v[104:107], v[170:173], v[198:201], v[104:107]
	v_mfma_f32_16x16x32_bf16 v[96:99], v[178:181], v[198:201], v[96:99]
	v_mfma_f32_16x16x32_bf16 v[88:91], v[170:173], v[206:209], v[88:91]
	v_mfma_f32_16x16x32_bf16 v[80:83], v[178:181], v[206:209], v[80:83]
	v_mfma_f32_16x16x32_bf16 v[72:75], v[170:173], v[214:217], v[72:75]
	v_mfma_f32_16x16x32_bf16 v[64:67], v[178:181], v[214:217], v[64:67]
	s_barrier
	s_setprio 0
	s_add_i32 s10, s64, s19
	v_lshl_add_u64 v[190:191], s[46:47], 0, v[136:137]
	s_mov_b32 m0, s10
	ds_read_b128 v[182:185], v153 offset:16384
	ds_read_b128 v[186:189], v153 offset:17408
	ds_read_b128 v[194:197], v153 offset:18432
	ds_read_b128 v[198:201], v153 offset:19456
	ds_read_b128 v[202:205], v153 offset:20480
	ds_read_b128 v[206:209], v153 offset:21504
	ds_read_b128 v[210:213], v153 offset:22528
	ds_read_b128 v[214:217], v153 offset:23552
	global_load_lds_dwordx4 v[190:191], off
	s_add_i32 m0, s10, 0x2000
	s_add_u32 s10, s46, 0x40000
	v_lshl_add_u64 v[218:219], s[46:47], 0, v[132:133]
	s_addc_u32 s11, s47, 0
	s_add_i32 s64, s65, s19
	global_load_lds_dwordx4 v[218:219], off
	v_lshl_add_u64 v[220:221], s[10:11], 0, v[136:137]
	s_mov_b32 m0, s64
	v_lshl_add_u64 v[222:223], s[48:49], 0, v[134:135]
	global_load_lds_dwordx4 v[220:221], off
	s_add_i32 m0, s64, 0x2000
	v_lshl_add_u64 v[220:221], s[10:11], 0, v[132:133]
	global_load_lds_dwordx4 v[220:221], off
	s_mov_b32 m0, s51
	v_lshl_add_u64 v[220:221], s[48:49], 0, v[138:139]
	global_load_lds_dwordx4 v[220:221], off
	s_mov_b32 m0, s52
	s_nop 0
	global_load_lds_dwordx4 v[222:223], off
	s_waitcnt vmcnt(8)
	s_waitcnt lgkmcnt(0)
	s_setprio 1
	s_barrier
; #define PG8_STAGE(bufoff, gbase, voff) do { _Pragma("unroll") for (int _i = 0; _i < 2; ++_i) \
;         __builtin_amdgcn_global_load_lds((const unsigned*)((const char*)(gbase) + (voff)[_i]), (PG8_LAS unsigned*)(lds + (bufoff) + ldsw + _i * 8192), 16, 0, 0); } while (0)
; #define PG8_LDA(dst, b, h) do { _Pragma("unroll") for (int m = 0; m < 4; ++m) _Pragma("unroll") for (int k = 0; k < 2; ++k) dst[m][k] = *(const PG8_LAS bf16x8*)(lds + PG8_SA(b, h) + aoff + m * 2048 + k * 1024); } while (0)
; #define PG8_LDB(dst, b, h) do { _Pragma("unroll") for (int n = 0; n < 2; ++n) _Pragma("unroll") for (int k = 0; k < 2; ++k) dst[n][k] = *(const PG8_LAS bf16x8*)(lds + PG8_SB(b, h) + boff + n * 2048 + k * 1024); } while (0)
; #define PG8_MMA(ai, bj, At, Bt) do { __builtin_amdgcn_s_setprio(1); _Pragma("unroll") for (int m = 0; m < 4; ++m) _Pragma("unroll") for (int n = 0; n < 2; ++n) _Pragma("unroll") for (int k = 0; k < 2; ++k) \
;         acc[ai][bj][m][n] = __builtin_amdgcn_mfma_f32_16x16x32_bf16(Bt[n][k], At[m][k], acc[ai][bj][m][n], 0, 0, 0); __builtin_amdgcn_s_setprio(0); } while (0)
; #define PG8_WAIT_V(n) asm volatile("s_waitcnt vmcnt(" #n ")" ::: "memory")
; #define PG8_WAIT_L(n) asm volatile("s_waitcnt lgkmcnt(" #n ")" ::: "memory")
; #define PG8_BAR __builtin_amdgcn_s_barrier()
; #define PG8_SCHED __builtin_amdgcn_sched_barrier(0)
; template <class Epi, class Sched, bool ALIGN_EPI = false, bool SP2 = false>
; __device__ __forceinline__ void gemm_phase(PG8_LAS unsigned char* lds, const Gemm g, const Sched& S, const Epi& E) {
;     ...
;             PG8_WAIT_V(8); PG8_WAIT_L(0); PG8_BAR; PG8_MMA(1, 0, At, B0); PG8_MMA(1, 1, At, B1); PG8_BAR; PG8_SCHED;
;             PG8_LDB(B0, 1, 0); PG8_LDB(B1, 1, 1); PG8_SCHED; PG8_LDA(At, 1, 0); PG8_STAGE(PG8_SA(0, 1), a2 + hstep, voffA);
;             PG8_WAIT_V(8); PG8_WAIT_L(0); PG8_BAR; PG8_MMA(0, 0, At, B0); PG8_MMA(0, 1, At, B1); PG8_BAR; PG8_SCHED;
	v_mfma_f32_16x16x32_bf16 v[60:63], v[128:131], v[182:185], v[60:63]
	v_mfma_f32_16x16x32_bf16 v[52:55], v[158:161], v[182:185], v[52:55]
	v_mfma_f32_16x16x32_bf16 v[44:47], v[128:131], v[194:197], v[44:47]
	v_mfma_f32_16x16x32_bf16 v[36:39], v[158:161], v[194:197], v[36:39]
	v_mfma_f32_16x16x32_bf16 v[28:31], v[128:131], v[202:205], v[28:31]
	v_mfma_f32_16x16x32_bf16 v[20:23], v[158:161], v[202:205], v[20:23]
	v_mfma_f32_16x16x32_bf16 v[12:15], v[128:131], v[210:213], v[12:15]
	v_mfma_f32_16x16x32_bf16 v[4:7], v[158:161], v[210:213], v[4:7]
	v_mfma_f32_16x16x32_bf16 v[60:63], v[154:157], v[186:189], v[60:63]
	v_mfma_f32_16x16x32_bf16 v[52:55], v[162:165], v[186:189], v[52:55]
	v_mfma_f32_16x16x32_bf16 v[44:47], v[154:157], v[198:201], v[44:47]
	v_mfma_f32_16x16x32_bf16 v[36:39], v[162:165], v[198:201], v[36:39]
	v_mfma_f32_16x16x32_bf16 v[28:31], v[154:157], v[206:209], v[28:31]
	v_mfma_f32_16x16x32_bf16 v[20:23], v[162:165], v[206:209], v[20:23]
	v_mfma_f32_16x16x32_bf16 v[12:15], v[154:157], v[214:217], v[12:15]
	v_mfma_f32_16x16x32_bf16 v[4:7], v[162:165], v[214:217], v[4:7]
	s_setprio 0
	s_setprio 1
	v_mfma_f32_16x16x32_bf16 v[56:59], v[166:169], v[182:185], v[56:59]
	v_mfma_f32_16x16x32_bf16 v[48:51], v[174:177], v[182:185], v[48:51]
	v_mfma_f32_16x16x32_bf16 v[40:43], v[166:169], v[194:197], v[40:43]
	v_mfma_f32_16x16x32_bf16 v[32:35], v[174:177], v[194:197], v[32:35]
	v_mfma_f32_16x16x32_bf16 v[24:27], v[166:169], v[202:205], v[24:27]
	v_mfma_f32_16x16x32_bf16 v[16:19], v[174:177], v[202:205], v[16:19]
	v_mfma_f32_16x16x32_bf16 v[8:11], v[166:169], v[210:213], v[8:11]
	v_mfma_f32_16x16x32_bf16 v[0:3], v[174:177], v[210:213], v[0:3]
	v_mfma_f32_16x16x32_bf16 v[56:59], v[170:173], v[186:189], v[56:59]
	v_mfma_f32_16x16x32_bf16 v[48:51], v[178:181], v[186:189], v[48:51]
	v_mfma_f32_16x16x32_bf16 v[40:43], v[170:173], v[198:201], v[40:43]
	v_mfma_f32_16x16x32_bf16 v[32:35], v[178:181], v[198:201], v[32:35]
	v_mfma_f32_16x16x32_bf16 v[24:27], v[170:173], v[206:209], v[24:27]
	v_mfma_f32_16x16x32_bf16 v[16:19], v[178:181], v[206:209], v[16:19]
	v_mfma_f32_16x16x32_bf16 v[8:11], v[170:173], v[214:217], v[8:11]
	v_mfma_f32_16x16x32_bf16 v[0:3], v[178:181], v[214:217], v[0:3]
	s_barrier
	s_setprio 0
	s_add_i32 s64, 0, 0x18000
	v_add_u32_e32 v146, s64, v149
	s_add_i32 s65, 0, 0x1c000
	ds_read_b128 v[128:131], v146
	ds_read_b128 v[154:157], v146 offset:1024
	ds_read_b128 v[158:161], v146 offset:2048
	ds_read_b128 v[162:165], v146 offset:3072
	v_add_u32_e32 v146, s65, v149
	ds_read_b128 v[166:169], v146
	ds_read_b128 v[170:173], v146 offset:1024
	ds_read_b128 v[174:177], v146 offset:2048
	ds_read_b128 v[178:181], v146 offset:3072
	s_add_u32 s10, s48, 0x40000
	s_addc_u32 s11, s49, 0
	s_mov_b32 m0, s53
	v_lshl_add_u64 v[224:225], s[10:11], 0, v[138:139]
	ds_read_b128 v[182:185], v153 offset:32768
	ds_read_b128 v[186:189], v153 offset:33792
	ds_read_b128 v[194:197], v153 offset:34816
	ds_read_b128 v[198:201], v153 offset:35840
	ds_read_b128 v[202:205], v153 offset:36864
	ds_read_b128 v[206:209], v153 offset:37888
	ds_read_b128 v[210:213], v153 offset:38912
	ds_read_b128 v[214:217], v153 offset:39936
	global_load_lds_dwordx4 v[224:225], off
	s_mov_b32 m0, s54
	v_lshl_add_u64 v[224:225], s[10:11], 0, v[134:135]
	global_load_lds_dwordx4 v[224:225], off
	s_waitcnt vmcnt(8)
	s_waitcnt lgkmcnt(0)
	s_setprio 1
	s_barrier
	v_mfma_f32_16x16x32_bf16 v[124:127], v[128:131], v[182:185], v[124:127]
	v_mfma_f32_16x16x32_bf16 v[116:119], v[158:161], v[182:185], v[116:119]
	v_mfma_f32_16x16x32_bf16 v[108:111], v[128:131], v[194:197], v[108:111]
	v_mfma_f32_16x16x32_bf16 v[100:103], v[158:161], v[194:197], v[100:103]
	v_mfma_f32_16x16x32_bf16 v[92:95], v[128:131], v[202:205], v[92:95]
	v_mfma_f32_16x16x32_bf16 v[84:87], v[158:161], v[202:205], v[84:87]
	v_mfma_f32_16x16x32_bf16 v[76:79], v[128:131], v[210:213], v[76:79]
	v_mfma_f32_16x16x32_bf16 v[68:71], v[158:161], v[210:213], v[68:71]
	v_mfma_f32_16x16x32_bf16 v[124:127], v[154:157], v[186:189], v[124:127]
	v_mfma_f32_16x16x32_bf16 v[116:119], v[162:165], v[186:189], v[116:119]
	v_mfma_f32_16x16x32_bf16 v[108:111], v[154:157], v[198:201], v[108:111]
	v_mfma_f32_16x16x32_bf16 v[100:103], v[162:165], v[198:201], v[100:103]
	v_mfma_f32_16x16x32_bf16 v[92:95], v[154:157], v[206:209], v[92:95]
	v_mfma_f32_16x16x32_bf16 v[84:87], v[162:165], v[206:209], v[84:87]
	v_mfma_f32_16x16x32_bf16 v[76:79], v[154:157], v[214:217], v[76:79]
	v_mfma_f32_16x16x32_bf16 v[68:71], v[162:165], v[214:217], v[68:71]
	s_setprio 0
	s_setprio 1
	v_mfma_f32_16x16x32_bf16 v[120:123], v[166:169], v[182:185], v[120:123]
	v_mfma_f32_16x16x32_bf16 v[112:115], v[174:177], v[182:185], v[112:115]
	v_mfma_f32_16x16x32_bf16 v[104:107], v[166:169], v[194:197], v[104:107]
	v_mfma_f32_16x16x32_bf16 v[96:99], v[174:177], v[194:197], v[96:99]
	v_mfma_f32_16x16x32_bf16 v[88:91], v[166:169], v[202:205], v[88:91]
	v_mfma_f32_16x16x32_bf16 v[80:83], v[174:177], v[202:205], v[80:83]
	v_mfma_f32_16x16x32_bf16 v[72:75], v[166:169], v[210:213], v[72:75]
	v_mfma_f32_16x16x32_bf16 v[64:67], v[174:177], v[210:213], v[64:67]
	v_mfma_f32_16x16x32_bf16 v[120:123], v[170:173], v[186:189], v[120:123]
	v_mfma_f32_16x16x32_bf16 v[112:115], v[178:181], v[186:189], v[112:115]
	v_mfma_f32_16x16x32_bf16 v[104:107], v[170:173], v[198:201], v[104:107]
	v_mfma_f32_16x16x32_bf16 v[96:99], v[178:181], v[198:201], v[96:99]
	v_mfma_f32_16x16x32_bf16 v[88:91], v[170:173], v[206:209], v[88:91]
	v_mfma_f32_16x16x32_bf16 v[80:83], v[178:181], v[206:209], v[80:83]
	v_mfma_f32_16x16x32_bf16 v[72:75], v[170:173], v[214:217], v[72:75]
	v_mfma_f32_16x16x32_bf16 v[64:67], v[178:181], v[214:217], v[64:67]
	s_barrier
; #define PG8_STAGE(bufoff, gbase, voff) do { _Pragma("unroll") for (int _i = 0; _i < 2; ++_i) \
;         __builtin_amdgcn_global_load_lds((const unsigned*)((const char*)(gbase) + (voff)[_i]), (PG8_LAS unsigned*)(lds + (bufoff) + ldsw + _i * 8192), 16, 0, 0); } while (0)
; #define PG8_LDA(dst, b, h) do { _Pragma("unroll") for (int m = 0; m < 4; ++m) _Pragma("unroll") for (int k = 0; k < 2; ++k) dst[m][k] = *(const PG8_LAS bf16x8*)(lds + PG8_SA(b, h) + aoff + m * 2048 + k * 1024); } while (0)
; #define PG8_MMA(ai, bj, At, Bt) do { __builtin_amdgcn_s_setprio(1); _Pragma("unroll") for (int m = 0; m < 4; ++m) _Pragma("unroll") for (int n = 0; n < 2; ++n) _Pragma("unroll") for (int k = 0; k < 2; ++k) \
;         acc[ai][bj][m][n] = __builtin_amdgcn_mfma_f32_16x16x32_bf16(Bt[n][k], At[m][k], acc[ai][bj][m][n], 0, 0, 0); __builtin_amdgcn_s_setprio(0); } while (0)
; #define PG8_WAIT_V(n) asm volatile("s_waitcnt vmcnt(" #n ")" ::: "memory")
; #define PG8_WAIT_L(n) asm volatile("s_waitcnt lgkmcnt(" #n ")" ::: "memory")
; #define PG8_BAR __builtin_amdgcn_s_barrier()
; #define PG8_SCHED __builtin_amdgcn_sched_barrier(0)
; template <class Epi, class Sched, bool ALIGN_EPI = false, bool SP2 = false>
; __device__ __forceinline__ void gemm_phase(PG8_LAS unsigned char* lds, const Gemm g, const Sched& S, const Epi& E) {
;     ...
;             PG8_LDA(At, 1, 1); PG8_STAGE(PG8_SB(1, 0), b3, voffB); PG8_STAGE(PG8_SB(1, 1), b3 + hstep, voffB); PG8_STAGE(PG8_SA(1, 0), a3, voffA);
;             PG8_WAIT_V(8); PG8_WAIT_L(0); PG8_BAR; PG8_MMA(1, 0, At, B0); PG8_MMA(1, 1, At, B1); PG8_BAR; PG8_SCHED;
;     ...
;         if constexpr (ALIGN_EPI) { if (wr == 0) PG8_BAR; }
	s_setprio 0
	s_add_i32 s10, s64, s19
	v_lshl_add_u64 v[190:191], v[190:191], 0, s[36:37]
	s_mov_b32 m0, s10
	ds_read_b128 v[182:185], v153 offset:49152
	ds_read_b128 v[186:189], v153 offset:50176
	ds_read_b128 v[194:197], v153 offset:51200
	ds_read_b128 v[198:201], v153 offset:52224
	ds_read_b128 v[202:205], v153 offset:53248
	ds_read_b128 v[206:209], v153 offset:54272
	ds_read_b128 v[210:213], v153 offset:55296
	ds_read_b128 v[214:217], v153 offset:56320
	global_load_lds_dwordx4 v[190:191], off
	s_add_i32 m0, s10, 0x2000
	s_add_u32 s10, s46, 0x40080
	v_lshl_add_u64 v[190:191], v[218:219], 0, s[36:37]
	s_addc_u32 s11, s47, 0
	s_add_i32 s46, s65, s19
	global_load_lds_dwordx4 v[190:191], off
	s_mov_b32 m0, s46
	v_lshl_add_u64 v[190:191], s[10:11], 0, v[136:137]
	global_load_lds_dwordx4 v[190:191], off
	s_add_i32 m0, s46, 0x2000
	v_lshl_add_u64 v[190:191], s[10:11], 0, v[132:133]
	global_load_lds_dwordx4 v[190:191], off
	s_mov_b32 m0, s20
	v_lshl_add_u64 v[190:191], v[220:221], 0, s[36:37]
	global_load_lds_dwordx4 v[190:191], off
	s_mov_b32 m0, s55
	v_lshl_add_u64 v[190:191], v[222:223], 0, s[36:37]
	global_load_lds_dwordx4 v[190:191], off
	s_waitcnt vmcnt(8)
	s_waitcnt lgkmcnt(0)
	s_setprio 1
	s_barrier
	v_mfma_f32_16x16x32_bf16 v[60:63], v[128:131], v[182:185], v[60:63]
	v_mfma_f32_16x16x32_bf16 v[52:55], v[158:161], v[182:185], v[52:55]
	v_mfma_f32_16x16x32_bf16 v[44:47], v[128:131], v[194:197], v[44:47]
	v_mfma_f32_16x16x32_bf16 v[36:39], v[158:161], v[194:197], v[36:39]
	v_mfma_f32_16x16x32_bf16 v[28:31], v[128:131], v[202:205], v[28:31]
	v_mfma_f32_16x16x32_bf16 v[20:23], v[158:161], v[202:205], v[20:23]
	v_mfma_f32_16x16x32_bf16 v[12:15], v[128:131], v[210:213], v[12:15]
	v_mfma_f32_16x16x32_bf16 v[4:7], v[158:161], v[210:213], v[4:7]
	v_mfma_f32_16x16x32_bf16 v[60:63], v[154:157], v[186:189], v[60:63]
	v_mfma_f32_16x16x32_bf16 v[52:55], v[162:165], v[186:189], v[52:55]
	v_mfma_f32_16x16x32_bf16 v[44:47], v[154:157], v[198:201], v[44:47]
	v_mfma_f32_16x16x32_bf16 v[36:39], v[162:165], v[198:201], v[36:39]
	v_mfma_f32_16x16x32_bf16 v[28:31], v[154:157], v[206:209], v[28:31]
	v_mfma_f32_16x16x32_bf16 v[20:23], v[162:165], v[206:209], v[20:23]
	v_mfma_f32_16x16x32_bf16 v[12:15], v[154:157], v[214:217], v[12:15]
	v_mfma_f32_16x16x32_bf16 v[4:7], v[162:165], v[214:217], v[4:7]
	s_setprio 0
	s_setprio 1
	v_mfma_f32_16x16x32_bf16 v[56:59], v[166:169], v[182:185], v[56:59]
	v_mfma_f32_16x16x32_bf16 v[48:51], v[174:177], v[182:185], v[48:51]
	v_mfma_f32_16x16x32_bf16 v[40:43], v[166:169], v[194:197], v[40:43]
	v_mfma_f32_16x16x32_bf16 v[32:35], v[174:177], v[194:197], v[32:35]
	v_mfma_f32_16x16x32_bf16 v[24:27], v[166:169], v[202:205], v[24:27]
	v_mfma_f32_16x16x32_bf16 v[16:19], v[174:177], v[202:205], v[16:19]
	v_mfma_f32_16x16x32_bf16 v[8:11], v[166:169], v[210:213], v[8:11]
	v_mfma_f32_16x16x32_bf16 v[0:3], v[174:177], v[210:213], v[0:3]
	v_mfma_f32_16x16x32_bf16 v[56:59], v[170:173], v[186:189], v[56:59]
	v_mfma_f32_16x16x32_bf16 v[48:51], v[178:181], v[186:189], v[48:51]
	v_mfma_f32_16x16x32_bf16 v[40:43], v[170:173], v[198:201], v[40:43]
	v_mfma_f32_16x16x32_bf16 v[32:35], v[178:181], v[198:201], v[32:35]
	v_mfma_f32_16x16x32_bf16 v[24:27], v[170:173], v[206:209], v[24:27]
	v_mfma_f32_16x16x32_bf16 v[16:19], v[178:181], v[206:209], v[16:19]
	v_mfma_f32_16x16x32_bf16 v[8:11], v[170:173], v[214:217], v[8:11]
	v_mfma_f32_16x16x32_bf16 v[0:3], v[178:181], v[214:217], v[0:3]
	s_barrier
	s_setprio 0
	s_add_i32 s63, s63, 2
	s_add_u32 s44, s44, 0x100
	s_addc_u32 s45, s45, 0
	s_add_u32 s61, s61, 0x100
	s_addc_u32 s62, s62, 0
	s_cmp_gt_u32 s63, 13
	s_cbranch_scc0 .LBB0_577
	s_and_b64 vcc, exec, s[24:25]
	s_cbranch_vccz .LBB0_580
	s_barrier
